# hand-written MLA q_b/kv_b projection phases (P3/P19): LDS-DMA small-K GEMM with cross-tile prefetch and hand epilogue
# speedup vs baseline: 1.1252x; 1.0158x over previous
.LBB0_865:
	s_cmp_gt_i32 s44, 3
	s_waitcnt lgkmcnt(0)
	s_cselect_b64 s[2:3], -1, 0
	s_cmp_lt_i32 s45, 4
	s_cselect_b64 s[4:5], -1, 0
	s_or_b64 s[2:3], s[2:3], s[4:5]
	s_and_b64 vcc, exec, s[2:3]
	s_cbranch_vccnz .LBB0_1194
	s_mov_b32 s28, s22
	s_and_b32 s2, s42, 7
	s_cmp_lg_u32 s2, 0
	s_cbranch_scc1 .Lmq3_vb
	s_and_b32 s2, s22, 7
	s_ashr_i32 s3, s42, 3
	s_mul_i32 s2, s3, s2
	s_ashr_i32 s3, s22, 3
	s_add_i32 s28, s2, s3
.Lmq3_vb:
	v_mbcnt_hi_u32_b32 v206, -1, v210
	s_lshr_b32 s29, s70, 6
	s_lshl_b32 s88, s70, 4
	s_and_b32 s90, s70, 0x40
	v_and_b32_e32 v245, 48, v206
	v_or_b32_e32 v245, s90, v245
	v_and_b32_e32 v207, 31, v206
	v_lshrrev_b32_e32 v208, 5, v206
	v_bfe_u32 v209, v206, 1, 3
	v_lshlrev_b32_e32 v211, 7, v207
	s_lshr_b32 s91, s70, 7
	s_lshl_b32 s31, s91, 6
	s_lshl_b32 s91, s91, 13
	s_lshl_b32 s34, s90, 1
	s_lshl_b32 s90, s90, 8
	s_add_u32 s90, s90, 0x8000
	v_xor_b32_e32 v212, v208, v209
	v_lshl_add_u32 v212, v212, 4, v211
	v_add_u32_e32 v184, s91, v212
	v_add_u32_e32 v188, s90, v212
	v_or_b32_e32 v212, 2, v208
	v_xor_b32_e32 v212, v212, v209
	v_lshl_add_u32 v212, v212, 4, v211
	v_add_u32_e32 v185, s91, v212
	v_add_u32_e32 v189, s90, v212
	v_or_b32_e32 v212, 4, v208
	v_xor_b32_e32 v212, v212, v209
	v_lshl_add_u32 v212, v212, 4, v211
	v_add_u32_e32 v186, s91, v212
	v_add_u32_e32 v190, s90, v212
	v_or_b32_e32 v212, 6, v208
	v_xor_b32_e32 v212, v212, v209
	v_lshl_add_u32 v212, v212, 4, v211
	v_add_u32_e32 v187, s91, v212
	v_add_u32_e32 v191, s90, v212
	v_lshlrev_b32_e32 v200, 3, v207
	v_lshlrev_b32_e32 v203, 2, v208
	s_mul_i32 s91, s29, 0x1200
	s_add_u32 s91, s91, 0x12000
	v_mul_u32_u24_e32 v212, 0x240, v208
	v_lshl_add_u32 v212, v207, 1, v212
	v_add_u32_e32 v201, s91, v212
	v_lshrrev_b32_e32 v204, 3, v206
	v_and_b32_e32 v212, 7, v206
	v_lshlrev_b32_e32 v205, 4, v212
	v_mul_u32_u24_e32 v212, 0x90, v204
	v_add3_u32 v202, v212, v205, s91
	s_load_dwordx2 s[4:5], s[0:1], 0x168
	s_load_dwordx2 s[6:7], s[0:1], 0xd0
	s_load_dwordx2 s[8:9], s[0:1], 0x210
	s_load_dwordx2 s[10:11], s[0:1], 0x148
	s_load_dwordx2 s[12:13], s[0:1], 0x178
	s_lshl_b32 s96, s29, 3
	v_add_u32_e32 v206, s96, v204
	v_xor_b32_e32 v207, v245, v205
	v_lshl_add_u32 v192, v206, 9, v207
	v_mov_b32_e32 v193, 0
	v_add_u32_e32 v208, 64, v206
	v_lshl_add_u32 v194, v208, 9, v207
	v_mov_b32_e32 v195, 0
	v_add_u32_e32 v208, 128, v206
	v_lshl_add_u32 v196, v208, 9, v207
	v_mov_b32_e32 v197, 0
	v_add_u32_e32 v208, 192, v206
	v_lshl_add_u32 v198, v208, 9, v207
	v_mov_b32_e32 v199, 0
	s_mov_b32 s30, s28
	s_cmp_ge_u32 s30, 768
	s_cbranch_scc1 .Lmq3q_done
	s_waitcnt lgkmcnt(0)
	s_mul_hi_u32 s35, s30, 0xaaaaaaab
	s_lshr_b32 s35, s35, 2
	s_mul_i32 s36, s35, 6
	s_sub_u32 s36, s30, s36
	s_lshl_b32 s98, s35, 17
	s_add_u32 s16, s4, s98
	s_addc_u32 s17, s5, 0
	s_lshl_b32 s98, s36, 17
	s_add_u32 s18, s6, s98
	s_addc_u32 s19, s7, 0
	s_add_u32 m0, s88, 0
	v_lshl_add_u64 v[152:153], v[192:193], 0, s[16:17]
	global_load_lds_dwordx4 v[152:153], off
	s_add_u32 m0, s88, 32768
	v_lshl_add_u64 v[154:155], v[192:193], 0, s[18:19]
	global_load_lds_dwordx4 v[154:155], off
	s_add_u32 m0, s88, 8192
	v_lshl_add_u64 v[156:157], v[194:195], 0, s[16:17]
	global_load_lds_dwordx4 v[156:157], off
	s_add_u32 m0, s88, 40960
	v_lshl_add_u64 v[152:153], v[194:195], 0, s[18:19]
	global_load_lds_dwordx4 v[152:153], off
	s_add_u32 m0, s88, 16384
	v_lshl_add_u64 v[154:155], v[196:197], 0, s[16:17]
	global_load_lds_dwordx4 v[154:155], off
	s_add_u32 m0, s88, 49152
	v_lshl_add_u64 v[156:157], v[196:197], 0, s[18:19]
	global_load_lds_dwordx4 v[156:157], off
	s_add_u32 m0, s88, 24576
	v_lshl_add_u64 v[152:153], v[198:199], 0, s[16:17]
	global_load_lds_dwordx4 v[152:153], off
	s_add_u32 m0, s88, 57344
	v_lshl_add_u64 v[154:155], v[198:199], 0, s[18:19]
	global_load_lds_dwordx4 v[154:155], off
.Lmq3q_tile:
	s_mul_hi_u32 s35, s30, 0xaaaaaaab
	s_lshr_b32 s35, s35, 2
	s_mul_i32 s36, s35, 6
	s_sub_u32 s36, s30, s36
	s_lshl_b32 s92, s35, 8
	s_add_u32 s92, s92, s31
	s_lshl_b32 s93, s36, 8
	s_add_u32 s93, s93, s34
	s_lshl_b32 s96, s92, 2
	v_lshl_add_u32 v212, v203, 2, s96
	s_waitcnt vmcnt(0)
	s_barrier
	s_add_u32 s20, s16, 128
	s_addc_u32 s21, s17, 0
	s_add_u32 s24, s18, 128
	s_addc_u32 s25, s19, 0
	s_add_u32 m0, s88, 65536
	v_lshl_add_u64 v[152:153], v[192:193], 0, s[20:21]
	global_load_lds_dwordx4 v[152:153], off
	s_add_u32 m0, s88, 98304
	v_lshl_add_u64 v[154:155], v[192:193], 0, s[24:25]
	global_load_lds_dwordx4 v[154:155], off
	s_add_u32 m0, s88, 73728
	v_lshl_add_u64 v[156:157], v[194:195], 0, s[20:21]
	global_load_lds_dwordx4 v[156:157], off
	s_add_u32 m0, s88, 106496
	v_lshl_add_u64 v[152:153], v[194:195], 0, s[24:25]
	global_load_lds_dwordx4 v[152:153], off
	s_add_u32 m0, s88, 81920
	v_lshl_add_u64 v[154:155], v[196:197], 0, s[20:21]
	global_load_lds_dwordx4 v[154:155], off
	s_add_u32 m0, s88, 114688
	v_lshl_add_u64 v[156:157], v[196:197], 0, s[24:25]
	global_load_lds_dwordx4 v[156:157], off
	s_add_u32 m0, s88, 90112
	v_lshl_add_u64 v[152:153], v[198:199], 0, s[20:21]
	global_load_lds_dwordx4 v[152:153], off
	s_add_u32 m0, s88, 122880
	v_lshl_add_u64 v[154:155], v[198:199], 0, s[24:25]
	global_load_lds_dwordx4 v[154:155], off
	global_load_dword v213, v212, s[8:9] offset:0
	global_load_dword v214, v212, s[8:9] offset:4
	global_load_dword v215, v212, s[8:9] offset:8
	global_load_dword v216, v212, s[8:9] offset:12
	global_load_dword v217, v212, s[8:9] offset:32
	global_load_dword v218, v212, s[8:9] offset:36
	global_load_dword v219, v212, s[8:9] offset:40
	global_load_dword v220, v212, s[8:9] offset:44
	global_load_dword v221, v212, s[8:9] offset:64
	global_load_dword v222, v212, s[8:9] offset:68
	global_load_dword v223, v212, s[8:9] offset:72
	global_load_dword v224, v212, s[8:9] offset:76
	global_load_dword v225, v212, s[8:9] offset:96
	global_load_dword v226, v212, s[8:9] offset:100
	global_load_dword v227, v212, s[8:9] offset:104
	global_load_dword v228, v212, s[8:9] offset:108
	global_load_dword v229, v212, s[8:9] offset:128
	global_load_dword v230, v212, s[8:9] offset:132
	global_load_dword v231, v212, s[8:9] offset:136
	global_load_dword v232, v212, s[8:9] offset:140
	global_load_dword v233, v212, s[8:9] offset:160
	global_load_dword v234, v212, s[8:9] offset:164
	global_load_dword v235, v212, s[8:9] offset:168
	global_load_dword v236, v212, s[8:9] offset:172
	global_load_dword v237, v212, s[8:9] offset:192
	global_load_dword v238, v212, s[8:9] offset:196
	global_load_dword v239, v212, s[8:9] offset:200
	global_load_dword v240, v212, s[8:9] offset:204
	global_load_dword v241, v212, s[8:9] offset:224
	global_load_dword v242, v212, s[8:9] offset:228
	global_load_dword v243, v212, s[8:9] offset:232
	global_load_dword v244, v212, s[8:9] offset:236
	ds_read_b128 v[160:163], v184
	ds_read_b128 v[168:171], v188
	ds_read_b128 v[164:167], v184 offset:4096
	ds_read_b128 v[172:175], v188 offset:4096
	ds_read_b128 v[176:179], v188 offset:8192
	ds_read_b128 v[180:183], v188 offset:12288
	ds_read_b128 v[128:131], v185
	ds_read_b128 v[136:139], v189
	ds_read_b128 v[132:135], v185 offset:4096
	ds_read_b128 v[140:143], v189 offset:4096
	ds_read_b128 v[144:147], v189 offset:8192
	ds_read_b128 v[148:151], v189 offset:12288
	s_waitcnt lgkmcnt(6)
	v_mfma_f32_32x32x16_bf16 v[112:127], v[160:163], v[168:171], 0
	v_mfma_f32_32x32x16_bf16 v[48:63], v[164:167], v[168:171], 0
	v_mfma_f32_32x32x16_bf16 v[96:111], v[160:163], v[172:175], 0
	v_mfma_f32_32x32x16_bf16 v[32:47], v[164:167], v[172:175], 0
	v_mfma_f32_32x32x16_bf16 v[80:95], v[160:163], v[176:179], 0
	v_mfma_f32_32x32x16_bf16 v[16:31], v[164:167], v[176:179], 0
	v_mfma_f32_32x32x16_bf16 v[64:79], v[160:163], v[180:183], 0
	v_mfma_f32_32x32x16_bf16 v[0:15], v[164:167], v[180:183], 0
	ds_read_b128 v[160:163], v186
	ds_read_b128 v[168:171], v190
	ds_read_b128 v[164:167], v186 offset:4096
	ds_read_b128 v[172:175], v190 offset:4096
	ds_read_b128 v[176:179], v190 offset:8192
	ds_read_b128 v[180:183], v190 offset:12288
	s_waitcnt lgkmcnt(6)
	v_mfma_f32_32x32x16_bf16 v[112:127], v[128:131], v[136:139], v[112:127]
	v_mfma_f32_32x32x16_bf16 v[48:63], v[132:135], v[136:139], v[48:63]
	v_mfma_f32_32x32x16_bf16 v[96:111], v[128:131], v[140:143], v[96:111]
	v_mfma_f32_32x32x16_bf16 v[32:47], v[132:135], v[140:143], v[32:47]
	v_mfma_f32_32x32x16_bf16 v[80:95], v[128:131], v[144:147], v[80:95]
	v_mfma_f32_32x32x16_bf16 v[16:31], v[132:135], v[144:147], v[16:31]
	v_mfma_f32_32x32x16_bf16 v[64:79], v[128:131], v[148:151], v[64:79]
	v_mfma_f32_32x32x16_bf16 v[0:15], v[132:135], v[148:151], v[0:15]
	ds_read_b128 v[128:131], v187
	ds_read_b128 v[136:139], v191
	ds_read_b128 v[132:135], v187 offset:4096
	ds_read_b128 v[140:143], v191 offset:4096
	ds_read_b128 v[144:147], v191 offset:8192
	ds_read_b128 v[148:151], v191 offset:12288
	s_waitcnt lgkmcnt(6)
	v_mfma_f32_32x32x16_bf16 v[112:127], v[160:163], v[168:171], v[112:127]
	v_mfma_f32_32x32x16_bf16 v[48:63], v[164:167], v[168:171], v[48:63]
	v_mfma_f32_32x32x16_bf16 v[96:111], v[160:163], v[172:175], v[96:111]
	v_mfma_f32_32x32x16_bf16 v[32:47], v[164:167], v[172:175], v[32:47]
	v_mfma_f32_32x32x16_bf16 v[80:95], v[160:163], v[176:179], v[80:95]
	v_mfma_f32_32x32x16_bf16 v[16:31], v[164:167], v[176:179], v[16:31]
	v_mfma_f32_32x32x16_bf16 v[64:79], v[160:163], v[180:183], v[64:79]
	v_mfma_f32_32x32x16_bf16 v[0:15], v[164:167], v[180:183], v[0:15]
	s_waitcnt vmcnt(0) lgkmcnt(0)
	s_barrier
	v_xor_b32_e32 v184, 0x10000, v184
	v_xor_b32_e32 v188, 0x10000, v188
	ds_read_b128 v[160:163], v184
	ds_read_b128 v[168:171], v188
	ds_read_b128 v[164:167], v184 offset:4096
	ds_read_b128 v[172:175], v188 offset:4096
	ds_read_b128 v[176:179], v188 offset:8192
	ds_read_b128 v[180:183], v188 offset:12288
	s_add_u32 s20, s16, 256
	s_addc_u32 s21, s17, 0
	s_add_u32 s24, s18, 256
	s_addc_u32 s25, s19, 0
	v_mfma_f32_32x32x16_bf16 v[112:127], v[128:131], v[136:139], v[112:127]
	v_xor_b32_e32 v185, 0x10000, v185
	v_xor_b32_e32 v189, 0x10000, v189
	s_add_u32 m0, s88, 0
	v_lshl_add_u64 v[152:153], v[192:193], 0, s[20:21]
	global_load_lds_dwordx4 v[152:153], off
	v_mfma_f32_32x32x16_bf16 v[48:63], v[132:135], v[136:139], v[48:63]
	v_xor_b32_e32 v186, 0x10000, v186
	v_xor_b32_e32 v190, 0x10000, v190
	s_add_u32 m0, s88, 32768
	v_lshl_add_u64 v[154:155], v[192:193], 0, s[24:25]
	global_load_lds_dwordx4 v[154:155], off
	v_mfma_f32_32x32x16_bf16 v[96:111], v[128:131], v[140:143], v[96:111]
	v_xor_b32_e32 v187, 0x10000, v187
	v_xor_b32_e32 v191, 0x10000, v191
	s_add_u32 m0, s88, 8192
	v_lshl_add_u64 v[156:157], v[194:195], 0, s[20:21]
	global_load_lds_dwordx4 v[156:157], off
	v_mfma_f32_32x32x16_bf16 v[32:47], v[132:135], v[140:143], v[32:47]
	s_add_u32 m0, s88, 40960
	v_lshl_add_u64 v[152:153], v[194:195], 0, s[24:25]
	global_load_lds_dwordx4 v[152:153], off
	v_mfma_f32_32x32x16_bf16 v[80:95], v[128:131], v[144:147], v[80:95]
	s_add_u32 m0, s88, 16384
	v_lshl_add_u64 v[154:155], v[196:197], 0, s[20:21]
	global_load_lds_dwordx4 v[154:155], off
	v_mfma_f32_32x32x16_bf16 v[16:31], v[132:135], v[144:147], v[16:31]
	s_add_u32 m0, s88, 49152
	v_lshl_add_u64 v[156:157], v[196:197], 0, s[24:25]
	global_load_lds_dwordx4 v[156:157], off
	v_mfma_f32_32x32x16_bf16 v[64:79], v[128:131], v[148:151], v[64:79]
	s_add_u32 m0, s88, 24576
	v_lshl_add_u64 v[152:153], v[198:199], 0, s[20:21]
	global_load_lds_dwordx4 v[152:153], off
	v_mfma_f32_32x32x16_bf16 v[0:15], v[132:135], v[148:151], v[0:15]
	s_add_u32 m0, s88, 57344
	v_lshl_add_u64 v[154:155], v[198:199], 0, s[24:25]
	global_load_lds_dwordx4 v[154:155], off
	ds_read_b128 v[128:131], v185
	ds_read_b128 v[136:139], v189
	ds_read_b128 v[132:135], v185 offset:4096
	ds_read_b128 v[140:143], v189 offset:4096
	ds_read_b128 v[144:147], v189 offset:8192
	ds_read_b128 v[148:151], v189 offset:12288
	s_waitcnt lgkmcnt(6)
	v_mfma_f32_32x32x16_bf16 v[112:127], v[160:163], v[168:171], v[112:127]
	v_mfma_f32_32x32x16_bf16 v[48:63], v[164:167], v[168:171], v[48:63]
	v_mfma_f32_32x32x16_bf16 v[96:111], v[160:163], v[172:175], v[96:111]
	v_mfma_f32_32x32x16_bf16 v[32:47], v[164:167], v[172:175], v[32:47]
	v_mfma_f32_32x32x16_bf16 v[80:95], v[160:163], v[176:179], v[80:95]
	v_mfma_f32_32x32x16_bf16 v[16:31], v[164:167], v[176:179], v[16:31]
	v_mfma_f32_32x32x16_bf16 v[64:79], v[160:163], v[180:183], v[64:79]
	v_mfma_f32_32x32x16_bf16 v[0:15], v[164:167], v[180:183], v[0:15]
	ds_read_b128 v[160:163], v186
	ds_read_b128 v[168:171], v190
	ds_read_b128 v[164:167], v186 offset:4096
	ds_read_b128 v[172:175], v190 offset:4096
	ds_read_b128 v[176:179], v190 offset:8192
	ds_read_b128 v[180:183], v190 offset:12288
	s_waitcnt lgkmcnt(6)
	v_mfma_f32_32x32x16_bf16 v[112:127], v[128:131], v[136:139], v[112:127]
	v_mfma_f32_32x32x16_bf16 v[48:63], v[132:135], v[136:139], v[48:63]
	v_mfma_f32_32x32x16_bf16 v[96:111], v[128:131], v[140:143], v[96:111]
	v_mfma_f32_32x32x16_bf16 v[32:47], v[132:135], v[140:143], v[32:47]
	v_mfma_f32_32x32x16_bf16 v[80:95], v[128:131], v[144:147], v[80:95]
	v_mfma_f32_32x32x16_bf16 v[16:31], v[132:135], v[144:147], v[16:31]
	v_mfma_f32_32x32x16_bf16 v[64:79], v[128:131], v[148:151], v[64:79]
	v_mfma_f32_32x32x16_bf16 v[0:15], v[132:135], v[148:151], v[0:15]
	ds_read_b128 v[128:131], v187
	ds_read_b128 v[136:139], v191
	ds_read_b128 v[132:135], v187 offset:4096
	ds_read_b128 v[140:143], v191 offset:4096
	ds_read_b128 v[144:147], v191 offset:8192
	ds_read_b128 v[148:151], v191 offset:12288
	s_waitcnt lgkmcnt(6)
	v_mfma_f32_32x32x16_bf16 v[112:127], v[160:163], v[168:171], v[112:127]
	v_mfma_f32_32x32x16_bf16 v[48:63], v[164:167], v[168:171], v[48:63]
	v_mfma_f32_32x32x16_bf16 v[96:111], v[160:163], v[172:175], v[96:111]
	v_mfma_f32_32x32x16_bf16 v[32:47], v[164:167], v[172:175], v[32:47]
	v_mfma_f32_32x32x16_bf16 v[80:95], v[160:163], v[176:179], v[80:95]
	v_mfma_f32_32x32x16_bf16 v[16:31], v[164:167], v[176:179], v[16:31]
	v_mfma_f32_32x32x16_bf16 v[64:79], v[160:163], v[180:183], v[64:79]
	v_mfma_f32_32x32x16_bf16 v[0:15], v[164:167], v[180:183], v[0:15]
	s_waitcnt vmcnt(0) lgkmcnt(0)
	s_barrier
	v_xor_b32_e32 v184, 0x10000, v184
	v_xor_b32_e32 v188, 0x10000, v188
	ds_read_b128 v[160:163], v184
	ds_read_b128 v[168:171], v188
	ds_read_b128 v[164:167], v184 offset:4096
	ds_read_b128 v[172:175], v188 offset:4096
	ds_read_b128 v[176:179], v188 offset:8192
	ds_read_b128 v[180:183], v188 offset:12288
	s_add_u32 s20, s16, 384
	s_addc_u32 s21, s17, 0
	s_add_u32 s24, s18, 384
	s_addc_u32 s25, s19, 0
	v_mfma_f32_32x32x16_bf16 v[112:127], v[128:131], v[136:139], v[112:127]
	v_xor_b32_e32 v185, 0x10000, v185
	v_xor_b32_e32 v189, 0x10000, v189
	s_add_u32 m0, s88, 65536
	v_lshl_add_u64 v[152:153], v[192:193], 0, s[20:21]
	global_load_lds_dwordx4 v[152:153], off
	v_mfma_f32_32x32x16_bf16 v[48:63], v[132:135], v[136:139], v[48:63]
	v_xor_b32_e32 v186, 0x10000, v186
	v_xor_b32_e32 v190, 0x10000, v190
	s_add_u32 m0, s88, 98304
	v_lshl_add_u64 v[154:155], v[192:193], 0, s[24:25]
	global_load_lds_dwordx4 v[154:155], off
	v_mfma_f32_32x32x16_bf16 v[96:111], v[128:131], v[140:143], v[96:111]
	v_xor_b32_e32 v187, 0x10000, v187
	v_xor_b32_e32 v191, 0x10000, v191
	s_add_u32 m0, s88, 73728
	v_lshl_add_u64 v[156:157], v[194:195], 0, s[20:21]
	global_load_lds_dwordx4 v[156:157], off
	v_mfma_f32_32x32x16_bf16 v[32:47], v[132:135], v[140:143], v[32:47]
	s_add_u32 m0, s88, 106496
	v_lshl_add_u64 v[152:153], v[194:195], 0, s[24:25]
	global_load_lds_dwordx4 v[152:153], off
	v_mfma_f32_32x32x16_bf16 v[80:95], v[128:131], v[144:147], v[80:95]
	s_add_u32 m0, s88, 81920
	v_lshl_add_u64 v[154:155], v[196:197], 0, s[20:21]
	global_load_lds_dwordx4 v[154:155], off
	v_mfma_f32_32x32x16_bf16 v[16:31], v[132:135], v[144:147], v[16:31]
	s_add_u32 m0, s88, 114688
	v_lshl_add_u64 v[156:157], v[196:197], 0, s[24:25]
	global_load_lds_dwordx4 v[156:157], off
	v_mfma_f32_32x32x16_bf16 v[64:79], v[128:131], v[148:151], v[64:79]
	s_add_u32 m0, s88, 90112
	v_lshl_add_u64 v[152:153], v[198:199], 0, s[20:21]
	global_load_lds_dwordx4 v[152:153], off
	v_mfma_f32_32x32x16_bf16 v[0:15], v[132:135], v[148:151], v[0:15]
	s_add_u32 m0, s88, 122880
	v_lshl_add_u64 v[154:155], v[198:199], 0, s[24:25]
	global_load_lds_dwordx4 v[154:155], off
	ds_read_b128 v[128:131], v185
	ds_read_b128 v[136:139], v189
	ds_read_b128 v[132:135], v185 offset:4096
	ds_read_b128 v[140:143], v189 offset:4096
	ds_read_b128 v[144:147], v189 offset:8192
	ds_read_b128 v[148:151], v189 offset:12288
	s_waitcnt lgkmcnt(6)
	v_mfma_f32_32x32x16_bf16 v[112:127], v[160:163], v[168:171], v[112:127]
	v_mfma_f32_32x32x16_bf16 v[48:63], v[164:167], v[168:171], v[48:63]
	v_mfma_f32_32x32x16_bf16 v[96:111], v[160:163], v[172:175], v[96:111]
	v_mfma_f32_32x32x16_bf16 v[32:47], v[164:167], v[172:175], v[32:47]
	v_mfma_f32_32x32x16_bf16 v[80:95], v[160:163], v[176:179], v[80:95]
	v_mfma_f32_32x32x16_bf16 v[16:31], v[164:167], v[176:179], v[16:31]
	v_mfma_f32_32x32x16_bf16 v[64:79], v[160:163], v[180:183], v[64:79]
	v_mfma_f32_32x32x16_bf16 v[0:15], v[164:167], v[180:183], v[0:15]
	ds_read_b128 v[160:163], v186
	ds_read_b128 v[168:171], v190
	ds_read_b128 v[164:167], v186 offset:4096
	ds_read_b128 v[172:175], v190 offset:4096
	ds_read_b128 v[176:179], v190 offset:8192
	ds_read_b128 v[180:183], v190 offset:12288
	s_waitcnt lgkmcnt(6)
	v_mfma_f32_32x32x16_bf16 v[112:127], v[128:131], v[136:139], v[112:127]
	v_mfma_f32_32x32x16_bf16 v[48:63], v[132:135], v[136:139], v[48:63]
	v_mfma_f32_32x32x16_bf16 v[96:111], v[128:131], v[140:143], v[96:111]
	v_mfma_f32_32x32x16_bf16 v[32:47], v[132:135], v[140:143], v[32:47]
	v_mfma_f32_32x32x16_bf16 v[80:95], v[128:131], v[144:147], v[80:95]
	v_mfma_f32_32x32x16_bf16 v[16:31], v[132:135], v[144:147], v[16:31]
	v_mfma_f32_32x32x16_bf16 v[64:79], v[128:131], v[148:151], v[64:79]
	v_mfma_f32_32x32x16_bf16 v[0:15], v[132:135], v[148:151], v[0:15]
	ds_read_b128 v[128:131], v187
	ds_read_b128 v[136:139], v191
	ds_read_b128 v[132:135], v187 offset:4096
	ds_read_b128 v[140:143], v191 offset:4096
	ds_read_b128 v[144:147], v191 offset:8192
	ds_read_b128 v[148:151], v191 offset:12288
	s_waitcnt lgkmcnt(6)
	v_mfma_f32_32x32x16_bf16 v[112:127], v[160:163], v[168:171], v[112:127]
	v_mfma_f32_32x32x16_bf16 v[48:63], v[164:167], v[168:171], v[48:63]
	v_mfma_f32_32x32x16_bf16 v[96:111], v[160:163], v[172:175], v[96:111]
	v_mfma_f32_32x32x16_bf16 v[32:47], v[164:167], v[172:175], v[32:47]
	v_mfma_f32_32x32x16_bf16 v[80:95], v[160:163], v[176:179], v[80:95]
	v_mfma_f32_32x32x16_bf16 v[16:31], v[164:167], v[176:179], v[16:31]
	v_mfma_f32_32x32x16_bf16 v[64:79], v[160:163], v[180:183], v[64:79]
	v_mfma_f32_32x32x16_bf16 v[0:15], v[164:167], v[180:183], v[0:15]
	s_waitcnt vmcnt(0) lgkmcnt(0)
	s_barrier
	v_xor_b32_e32 v184, 0x10000, v184
	v_xor_b32_e32 v188, 0x10000, v188
	ds_read_b128 v[160:163], v184
	ds_read_b128 v[168:171], v188
	ds_read_b128 v[164:167], v184 offset:4096
	ds_read_b128 v[172:175], v188 offset:4096
	ds_read_b128 v[176:179], v188 offset:8192
	ds_read_b128 v[180:183], v188 offset:12288
	s_add_u32 s37, s30, s42
	s_cmp_ge_u32 s37, 768
	s_cbranch_scc1 .Lmq3q_nonext2
	s_mul_hi_u32 s38, s37, 0xaaaaaaab
	s_lshr_b32 s38, s38, 2
	s_mul_i32 s39, s38, 6
	s_sub_u32 s39, s37, s39
	s_lshl_b32 s98, s38, 17
	s_add_u32 s16, s4, s98
	s_addc_u32 s17, s5, 0
	s_lshl_b32 s98, s39, 17
	s_add_u32 s18, s6, s98
	s_addc_u32 s19, s7, 0
	v_mfma_f32_32x32x16_bf16 v[112:127], v[128:131], v[136:139], v[112:127]
	v_xor_b32_e32 v185, 0x10000, v185
	v_xor_b32_e32 v189, 0x10000, v189
	s_add_u32 m0, s88, 0
	v_lshl_add_u64 v[152:153], v[192:193], 0, s[16:17]
	global_load_lds_dwordx4 v[152:153], off
	v_mfma_f32_32x32x16_bf16 v[48:63], v[132:135], v[136:139], v[48:63]
	v_xor_b32_e32 v186, 0x10000, v186
	v_xor_b32_e32 v190, 0x10000, v190
	s_add_u32 m0, s88, 32768
	v_lshl_add_u64 v[154:155], v[192:193], 0, s[18:19]
	global_load_lds_dwordx4 v[154:155], off
	v_mfma_f32_32x32x16_bf16 v[96:111], v[128:131], v[140:143], v[96:111]
	v_xor_b32_e32 v187, 0x10000, v187
	v_xor_b32_e32 v191, 0x10000, v191
	s_add_u32 m0, s88, 8192
	v_lshl_add_u64 v[156:157], v[194:195], 0, s[16:17]
	global_load_lds_dwordx4 v[156:157], off
	v_mfma_f32_32x32x16_bf16 v[32:47], v[132:135], v[140:143], v[32:47]
	s_add_u32 m0, s88, 40960
	v_lshl_add_u64 v[152:153], v[194:195], 0, s[18:19]
	global_load_lds_dwordx4 v[152:153], off
	v_mfma_f32_32x32x16_bf16 v[80:95], v[128:131], v[144:147], v[80:95]
	s_add_u32 m0, s88, 16384
	v_lshl_add_u64 v[154:155], v[196:197], 0, s[16:17]
	global_load_lds_dwordx4 v[154:155], off
	v_mfma_f32_32x32x16_bf16 v[16:31], v[132:135], v[144:147], v[16:31]
	s_add_u32 m0, s88, 49152
	v_lshl_add_u64 v[156:157], v[196:197], 0, s[18:19]
	global_load_lds_dwordx4 v[156:157], off
	v_mfma_f32_32x32x16_bf16 v[64:79], v[128:131], v[148:151], v[64:79]
	s_add_u32 m0, s88, 24576
	v_lshl_add_u64 v[152:153], v[198:199], 0, s[16:17]
	global_load_lds_dwordx4 v[152:153], off
	v_mfma_f32_32x32x16_bf16 v[0:15], v[132:135], v[148:151], v[0:15]
	s_add_u32 m0, s88, 57344
	v_lshl_add_u64 v[154:155], v[198:199], 0, s[18:19]
	global_load_lds_dwordx4 v[154:155], off
	s_branch .Lmq3q_join2
.Lmq3q_nonext2:
	v_mfma_f32_32x32x16_bf16 v[112:127], v[128:131], v[136:139], v[112:127]
	v_xor_b32_e32 v185, 0x10000, v185
	v_xor_b32_e32 v189, 0x10000, v189
	v_mfma_f32_32x32x16_bf16 v[48:63], v[132:135], v[136:139], v[48:63]
	v_xor_b32_e32 v186, 0x10000, v186
	v_xor_b32_e32 v190, 0x10000, v190
	v_mfma_f32_32x32x16_bf16 v[96:111], v[128:131], v[140:143], v[96:111]
	v_xor_b32_e32 v187, 0x10000, v187
	v_xor_b32_e32 v191, 0x10000, v191
	v_mfma_f32_32x32x16_bf16 v[32:47], v[132:135], v[140:143], v[32:47]
	v_mfma_f32_32x32x16_bf16 v[80:95], v[128:131], v[144:147], v[80:95]
	v_mfma_f32_32x32x16_bf16 v[16:31], v[132:135], v[144:147], v[16:31]
	v_mfma_f32_32x32x16_bf16 v[64:79], v[128:131], v[148:151], v[64:79]
	v_mfma_f32_32x32x16_bf16 v[0:15], v[132:135], v[148:151], v[0:15]
.Lmq3q_join2:
	ds_read_b128 v[128:131], v185
	ds_read_b128 v[136:139], v189
	ds_read_b128 v[132:135], v185 offset:4096
	ds_read_b128 v[140:143], v189 offset:4096
	ds_read_b128 v[144:147], v189 offset:8192
	ds_read_b128 v[148:151], v189 offset:12288
	s_waitcnt lgkmcnt(6)
	v_mfma_f32_32x32x16_bf16 v[112:127], v[160:163], v[168:171], v[112:127]
	v_mfma_f32_32x32x16_bf16 v[48:63], v[164:167], v[168:171], v[48:63]
	v_mfma_f32_32x32x16_bf16 v[96:111], v[160:163], v[172:175], v[96:111]
	v_mfma_f32_32x32x16_bf16 v[32:47], v[164:167], v[172:175], v[32:47]
	v_mfma_f32_32x32x16_bf16 v[80:95], v[160:163], v[176:179], v[80:95]
	v_mfma_f32_32x32x16_bf16 v[16:31], v[164:167], v[176:179], v[16:31]
	v_mfma_f32_32x32x16_bf16 v[64:79], v[160:163], v[180:183], v[64:79]
	v_mfma_f32_32x32x16_bf16 v[0:15], v[164:167], v[180:183], v[0:15]
	ds_read_b128 v[160:163], v186
	ds_read_b128 v[168:171], v190
	ds_read_b128 v[164:167], v186 offset:4096
	ds_read_b128 v[172:175], v190 offset:4096
	ds_read_b128 v[176:179], v190 offset:8192
	ds_read_b128 v[180:183], v190 offset:12288
	s_waitcnt lgkmcnt(6)
	v_mfma_f32_32x32x16_bf16 v[112:127], v[128:131], v[136:139], v[112:127]
	v_mfma_f32_32x32x16_bf16 v[48:63], v[132:135], v[136:139], v[48:63]
	v_mfma_f32_32x32x16_bf16 v[96:111], v[128:131], v[140:143], v[96:111]
	v_mfma_f32_32x32x16_bf16 v[32:47], v[132:135], v[140:143], v[32:47]
	v_mfma_f32_32x32x16_bf16 v[80:95], v[128:131], v[144:147], v[80:95]
	v_mfma_f32_32x32x16_bf16 v[16:31], v[132:135], v[144:147], v[16:31]
	v_mfma_f32_32x32x16_bf16 v[64:79], v[128:131], v[148:151], v[64:79]
	v_mfma_f32_32x32x16_bf16 v[0:15], v[132:135], v[148:151], v[0:15]
	ds_read_b128 v[128:131], v187
	ds_read_b128 v[136:139], v191
	ds_read_b128 v[132:135], v187 offset:4096
	ds_read_b128 v[140:143], v191 offset:4096
	ds_read_b128 v[144:147], v191 offset:8192
	ds_read_b128 v[148:151], v191 offset:12288
	s_waitcnt lgkmcnt(6)
	v_mfma_f32_32x32x16_bf16 v[112:127], v[160:163], v[168:171], v[112:127]
	v_mfma_f32_32x32x16_bf16 v[48:63], v[164:167], v[168:171], v[48:63]
	v_mfma_f32_32x32x16_bf16 v[96:111], v[160:163], v[172:175], v[96:111]
	v_mfma_f32_32x32x16_bf16 v[32:47], v[164:167], v[172:175], v[32:47]
	v_mfma_f32_32x32x16_bf16 v[80:95], v[160:163], v[176:179], v[80:95]
	v_mfma_f32_32x32x16_bf16 v[16:31], v[164:167], v[176:179], v[16:31]
	v_mfma_f32_32x32x16_bf16 v[64:79], v[160:163], v[180:183], v[64:79]
	v_mfma_f32_32x32x16_bf16 v[0:15], v[164:167], v[180:183], v[0:15]
	s_waitcnt vmcnt(0) lgkmcnt(0)
	s_barrier
	v_xor_b32_e32 v184, 0x10000, v184
	v_xor_b32_e32 v188, 0x10000, v188
	v_mfma_f32_32x32x16_bf16 v[112:127], v[128:131], v[136:139], v[112:127]
	v_xor_b32_e32 v185, 0x10000, v185
	v_xor_b32_e32 v189, 0x10000, v189
	v_mul_f32_e32 v213, 0x3b800000, v213
	v_mul_f32_e32 v214, 0x3b800000, v214
	v_mul_f32_e32 v215, 0x3b800000, v215
	v_mul_f32_e32 v216, 0x3b800000, v216
	v_add_f32_e32 v213, 0x358637bd, v213
	v_add_f32_e32 v214, 0x358637bd, v214
	v_add_f32_e32 v215, 0x358637bd, v215
	v_add_f32_e32 v216, 0x358637bd, v216
	v_rsq_f32_e32 v213, v213
	v_rsq_f32_e32 v214, v214
	v_rsq_f32_e32 v215, v215
	v_rsq_f32_e32 v216, v216
	v_mul_f32_e32 v213, 0x3dd53b94, v213
	v_mul_f32_e32 v214, 0x3dd53b94, v214
	v_mul_f32_e32 v215, 0x3dd53b94, v215
	v_mul_f32_e32 v216, 0x3dd53b94, v216
	v_mfma_f32_32x32x16_bf16 v[48:63], v[132:135], v[136:139], v[48:63]
	v_xor_b32_e32 v186, 0x10000, v186
	v_xor_b32_e32 v190, 0x10000, v190
	v_mul_f32_e32 v217, 0x3b800000, v217
	v_mul_f32_e32 v218, 0x3b800000, v218
	v_mul_f32_e32 v219, 0x3b800000, v219
	v_mul_f32_e32 v220, 0x3b800000, v220
	v_add_f32_e32 v217, 0x358637bd, v217
	v_add_f32_e32 v218, 0x358637bd, v218
	v_add_f32_e32 v219, 0x358637bd, v219
	v_add_f32_e32 v220, 0x358637bd, v220
	v_rsq_f32_e32 v217, v217
	v_rsq_f32_e32 v218, v218
	v_rsq_f32_e32 v219, v219
	v_rsq_f32_e32 v220, v220
	v_mul_f32_e32 v217, 0x3dd53b94, v217
	v_mul_f32_e32 v218, 0x3dd53b94, v218
	v_mul_f32_e32 v219, 0x3dd53b94, v219
	v_mul_f32_e32 v220, 0x3dd53b94, v220
	v_mfma_f32_32x32x16_bf16 v[96:111], v[128:131], v[140:143], v[96:111]
	v_xor_b32_e32 v187, 0x10000, v187
	v_xor_b32_e32 v191, 0x10000, v191
	v_mul_f32_e32 v221, 0x3b800000, v221
	v_mul_f32_e32 v222, 0x3b800000, v222
	v_mul_f32_e32 v223, 0x3b800000, v223
	v_mul_f32_e32 v224, 0x3b800000, v224
	v_add_f32_e32 v221, 0x358637bd, v221
	v_add_f32_e32 v222, 0x358637bd, v222
	v_add_f32_e32 v223, 0x358637bd, v223
	v_add_f32_e32 v224, 0x358637bd, v224
	v_rsq_f32_e32 v221, v221
	v_rsq_f32_e32 v222, v222
	v_rsq_f32_e32 v223, v223
	v_rsq_f32_e32 v224, v224
	v_mul_f32_e32 v221, 0x3dd53b94, v221
	v_mul_f32_e32 v222, 0x3dd53b94, v222
	v_mul_f32_e32 v223, 0x3dd53b94, v223
	v_mul_f32_e32 v224, 0x3dd53b94, v224
	v_mfma_f32_32x32x16_bf16 v[32:47], v[132:135], v[140:143], v[32:47]
	v_mul_f32_e32 v225, 0x3b800000, v225
	v_mul_f32_e32 v226, 0x3b800000, v226
	v_mul_f32_e32 v227, 0x3b800000, v227
	v_mul_f32_e32 v228, 0x3b800000, v228
	v_add_f32_e32 v225, 0x358637bd, v225
	v_add_f32_e32 v226, 0x358637bd, v226
	v_add_f32_e32 v227, 0x358637bd, v227
	v_add_f32_e32 v228, 0x358637bd, v228
	v_rsq_f32_e32 v225, v225
	v_rsq_f32_e32 v226, v226
	v_rsq_f32_e32 v227, v227
	v_rsq_f32_e32 v228, v228
	v_mul_f32_e32 v225, 0x3dd53b94, v225
	v_mul_f32_e32 v226, 0x3dd53b94, v226
	v_mul_f32_e32 v227, 0x3dd53b94, v227
	v_mul_f32_e32 v228, 0x3dd53b94, v228
	v_mfma_f32_32x32x16_bf16 v[80:95], v[128:131], v[144:147], v[80:95]
	v_mul_f32_e32 v229, 0x3b800000, v229
	v_mul_f32_e32 v230, 0x3b800000, v230
	v_mul_f32_e32 v231, 0x3b800000, v231
	v_mul_f32_e32 v232, 0x3b800000, v232
	v_add_f32_e32 v229, 0x358637bd, v229
	v_add_f32_e32 v230, 0x358637bd, v230
	v_add_f32_e32 v231, 0x358637bd, v231
	v_add_f32_e32 v232, 0x358637bd, v232
	v_rsq_f32_e32 v229, v229
	v_rsq_f32_e32 v230, v230
	v_rsq_f32_e32 v231, v231
	v_rsq_f32_e32 v232, v232
	v_mul_f32_e32 v229, 0x3dd53b94, v229
	v_mul_f32_e32 v230, 0x3dd53b94, v230
	v_mul_f32_e32 v231, 0x3dd53b94, v231
	v_mul_f32_e32 v232, 0x3dd53b94, v232
	v_mfma_f32_32x32x16_bf16 v[16:31], v[132:135], v[144:147], v[16:31]
	v_mul_f32_e32 v233, 0x3b800000, v233
	v_mul_f32_e32 v234, 0x3b800000, v234
	v_mul_f32_e32 v235, 0x3b800000, v235
	v_mul_f32_e32 v236, 0x3b800000, v236
	v_add_f32_e32 v233, 0x358637bd, v233
	v_add_f32_e32 v234, 0x358637bd, v234
	v_add_f32_e32 v235, 0x358637bd, v235
	v_add_f32_e32 v236, 0x358637bd, v236
	v_rsq_f32_e32 v233, v233
	v_rsq_f32_e32 v234, v234
	v_rsq_f32_e32 v235, v235
	v_rsq_f32_e32 v236, v236
	v_mul_f32_e32 v233, 0x3dd53b94, v233
	v_mul_f32_e32 v234, 0x3dd53b94, v234
	v_mul_f32_e32 v235, 0x3dd53b94, v235
	v_mul_f32_e32 v236, 0x3dd53b94, v236
	v_mfma_f32_32x32x16_bf16 v[64:79], v[128:131], v[148:151], v[64:79]
	v_mul_f32_e32 v237, 0x3b800000, v237
	v_mul_f32_e32 v238, 0x3b800000, v238
	v_mul_f32_e32 v239, 0x3b800000, v239
	v_mul_f32_e32 v240, 0x3b800000, v240
	v_add_f32_e32 v237, 0x358637bd, v237
	v_add_f32_e32 v238, 0x358637bd, v238
	v_add_f32_e32 v239, 0x358637bd, v239
	v_add_f32_e32 v240, 0x358637bd, v240
	v_rsq_f32_e32 v237, v237
	v_rsq_f32_e32 v238, v238
	v_rsq_f32_e32 v239, v239
	v_rsq_f32_e32 v240, v240
	v_mul_f32_e32 v237, 0x3dd53b94, v237
	v_mul_f32_e32 v238, 0x3dd53b94, v238
	v_mul_f32_e32 v239, 0x3dd53b94, v239
	v_mul_f32_e32 v240, 0x3dd53b94, v240
	v_mfma_f32_32x32x16_bf16 v[0:15], v[132:135], v[148:151], v[0:15]
	v_mul_f32_e32 v241, 0x3b800000, v241
	v_mul_f32_e32 v242, 0x3b800000, v242
	v_mul_f32_e32 v243, 0x3b800000, v243
	v_mul_f32_e32 v244, 0x3b800000, v244
	v_add_f32_e32 v241, 0x358637bd, v241
	v_add_f32_e32 v242, 0x358637bd, v242
	v_add_f32_e32 v243, 0x358637bd, v243
	v_add_f32_e32 v244, 0x358637bd, v244
	v_rsq_f32_e32 v241, v241
	v_rsq_f32_e32 v242, v242
	v_rsq_f32_e32 v243, v243
	v_rsq_f32_e32 v244, v244
	v_mul_f32_e32 v241, 0x3dd53b94, v241
	v_mul_f32_e32 v242, 0x3dd53b94, v242
	v_mul_f32_e32 v243, 0x3dd53b94, v243
	v_mul_f32_e32 v244, 0x3dd53b94, v244
	s_nop 7
	s_add_u32 s94, s92, 0
	s_add_u32 s95, s93, 0
	s_lshr_b32 s90, s95, 6
	s_lshr_b32 s96, s94, 12
	s_and_b32 s97, s94, 0xfff
	s_mul_i32 s91, s90, 11
	s_lshr_b32 s91, s91, 5
	s_mul_i32 s98, s91, 3
	s_sub_u32 s98, s90, s98
	s_mul_i32 s89, s96, 0xc00000
	s_mul_i32 s91, s91, 0x180000
	s_add_u32 s89, s89, s91
	s_lshl_b32 s91, s98, 7
	s_add_u32 s89, s89, s91
	s_mul_i32 s91, s97, 0x180
	s_add_u32 s89, s89, s91
	s_movk_i32 s99, 0x180
	s_mov_b64 s[2:3], s[12:13]
	s_cmp_eq_u32 s98, 2
	s_cbranch_scc1 .Lmq3q_e00_rope
.Lmq3q_e00_plain:
	v_mul_f32_e32 v206, v112, v213
	v_mul_f32_e32 v207, v96, v213
	v_cvt_pk_bf16_f32 v206, v206, v207
	ds_write_b16 v201, v206
	ds_write_b16_d16_hi v201, v206 offset:64
	v_mul_f32_e32 v208, v113, v214
	v_mul_f32_e32 v209, v97, v214
	v_cvt_pk_bf16_f32 v208, v208, v209
	ds_write_b16 v201, v208 offset:144
	ds_write_b16_d16_hi v201, v208 offset:208
	v_mul_f32_e32 v206, v114, v215
	v_mul_f32_e32 v207, v98, v215
	v_cvt_pk_bf16_f32 v206, v206, v207
	ds_write_b16 v201, v206 offset:288
	ds_write_b16_d16_hi v201, v206 offset:352
	v_mul_f32_e32 v208, v115, v216
	v_mul_f32_e32 v209, v99, v216
	v_cvt_pk_bf16_f32 v208, v208, v209
	ds_write_b16 v201, v208 offset:432
	ds_write_b16_d16_hi v201, v208 offset:496
	v_mul_f32_e32 v206, v116, v217
	v_mul_f32_e32 v207, v100, v217
	v_cvt_pk_bf16_f32 v206, v206, v207
	ds_write_b16 v201, v206 offset:1152
	ds_write_b16_d16_hi v201, v206 offset:1216
	v_mul_f32_e32 v208, v117, v218
	v_mul_f32_e32 v209, v101, v218
	v_cvt_pk_bf16_f32 v208, v208, v209
	ds_write_b16 v201, v208 offset:1296
	ds_write_b16_d16_hi v201, v208 offset:1360
	v_mul_f32_e32 v206, v118, v219
	v_mul_f32_e32 v207, v102, v219
	v_cvt_pk_bf16_f32 v206, v206, v207
	ds_write_b16 v201, v206 offset:1440
	ds_write_b16_d16_hi v201, v206 offset:1504
	v_mul_f32_e32 v208, v119, v220
	v_mul_f32_e32 v209, v103, v220
	v_cvt_pk_bf16_f32 v208, v208, v209
	ds_write_b16 v201, v208 offset:1584
	ds_write_b16_d16_hi v201, v208 offset:1648
	v_mul_f32_e32 v206, v120, v221
	v_mul_f32_e32 v207, v104, v221
	v_cvt_pk_bf16_f32 v206, v206, v207
	ds_write_b16 v201, v206 offset:2304
	ds_write_b16_d16_hi v201, v206 offset:2368
	v_mul_f32_e32 v208, v121, v222
	v_mul_f32_e32 v209, v105, v222
	v_cvt_pk_bf16_f32 v208, v208, v209
	ds_write_b16 v201, v208 offset:2448
	ds_write_b16_d16_hi v201, v208 offset:2512
	v_mul_f32_e32 v206, v122, v223
	v_mul_f32_e32 v207, v106, v223
	v_cvt_pk_bf16_f32 v206, v206, v207
	ds_write_b16 v201, v206 offset:2592
	ds_write_b16_d16_hi v201, v206 offset:2656
	v_mul_f32_e32 v208, v123, v224
	v_mul_f32_e32 v209, v107, v224
	v_cvt_pk_bf16_f32 v208, v208, v209
	ds_write_b16 v201, v208 offset:2736
	ds_write_b16_d16_hi v201, v208 offset:2800
	v_mul_f32_e32 v206, v124, v225
	v_mul_f32_e32 v207, v108, v225
	v_cvt_pk_bf16_f32 v206, v206, v207
	ds_write_b16 v201, v206 offset:3456
	ds_write_b16_d16_hi v201, v206 offset:3520
	v_mul_f32_e32 v208, v125, v226
	v_mul_f32_e32 v209, v109, v226
	v_cvt_pk_bf16_f32 v208, v208, v209
	ds_write_b16 v201, v208 offset:3600
	ds_write_b16_d16_hi v201, v208 offset:3664
	v_mul_f32_e32 v206, v126, v227
	v_mul_f32_e32 v207, v110, v227
	v_cvt_pk_bf16_f32 v206, v206, v207
	ds_write_b16 v201, v206 offset:3744
	ds_write_b16_d16_hi v201, v206 offset:3808
	v_mul_f32_e32 v208, v127, v228
	v_mul_f32_e32 v209, v111, v228
	v_cvt_pk_bf16_f32 v208, v208, v209
	ds_write_b16 v201, v208 offset:3888
	ds_write_b16_d16_hi v201, v208 offset:3952
	s_branch .Lmq3q_e00_st
.Lmq3q_e00_rope:
	v_add_u32_e32 v206, s94, v203
	v_lshlrev_b32_e32 v206, 8, v206
	v_add_u32_e32 v176, v206, v200
	v_mov_b32_e32 v177, 0
	v_lshl_add_u64 v[176:177], s[10:11], 0, v[176:177]
	global_load_dwordx2 v[128:129], v[176:177], off
	global_load_dwordx2 v[130:131], v[176:177], off offset:256
	global_load_dwordx2 v[132:133], v[176:177], off offset:512
	global_load_dwordx2 v[134:135], v[176:177], off offset:768
	global_load_dwordx2 v[136:137], v[176:177], off offset:2048
	global_load_dwordx2 v[138:139], v[176:177], off offset:2304
	global_load_dwordx2 v[140:141], v[176:177], off offset:2560
	global_load_dwordx2 v[142:143], v[176:177], off offset:2816
	v_add_co_u32_e32 v178, vcc, 0x1000, v176
	s_nop 1
	v_addc_co_u32_e32 v179, vcc, 0, v177, vcc
	global_load_dwordx2 v[144:145], v[178:179], off
	global_load_dwordx2 v[146:147], v[178:179], off offset:256
	global_load_dwordx2 v[148:149], v[178:179], off offset:512
	global_load_dwordx2 v[150:151], v[178:179], off offset:768
	global_load_dwordx2 v[152:153], v[178:179], off offset:2048
	global_load_dwordx2 v[154:155], v[178:179], off offset:2304
	global_load_dwordx2 v[156:157], v[178:179], off offset:2560
	global_load_dwordx2 v[158:159], v[178:179], off offset:2816
	v_mul_f32_e32 v208, v112, v213
	v_mul_f32_e32 v209, v96, v213
	s_waitcnt vmcnt(15)
	v_mul_f32_e32 v206, v209, v129
	v_mul_f32_e32 v207, v208, v129
	v_fma_f32 v206, v208, v128, -v206
	v_fma_f32 v207, v209, v128, v207
	v_cvt_pk_bf16_f32 v206, v206, v207
	ds_write_b16 v201, v206
	ds_write_b16_d16_hi v201, v206 offset:64
	v_mul_f32_e32 v208, v113, v214
	v_mul_f32_e32 v209, v97, v214
	s_waitcnt vmcnt(14)
	v_mul_f32_e32 v206, v209, v131
	v_mul_f32_e32 v207, v208, v131
	v_fma_f32 v206, v208, v130, -v206
	v_fma_f32 v207, v209, v130, v207
	v_cvt_pk_bf16_f32 v206, v206, v207
	ds_write_b16 v201, v206 offset:144
	ds_write_b16_d16_hi v201, v206 offset:208
	v_mul_f32_e32 v208, v114, v215
	v_mul_f32_e32 v209, v98, v215
	s_waitcnt vmcnt(13)
	v_mul_f32_e32 v206, v209, v133
	v_mul_f32_e32 v207, v208, v133
	v_fma_f32 v206, v208, v132, -v206
	v_fma_f32 v207, v209, v132, v207
	v_cvt_pk_bf16_f32 v206, v206, v207
	ds_write_b16 v201, v206 offset:288
	ds_write_b16_d16_hi v201, v206 offset:352
	v_mul_f32_e32 v208, v115, v216
	v_mul_f32_e32 v209, v99, v216
	s_waitcnt vmcnt(12)
	v_mul_f32_e32 v206, v209, v135
	v_mul_f32_e32 v207, v208, v135
	v_fma_f32 v206, v208, v134, -v206
	v_fma_f32 v207, v209, v134, v207
	v_cvt_pk_bf16_f32 v206, v206, v207
	ds_write_b16 v201, v206 offset:432
	ds_write_b16_d16_hi v201, v206 offset:496
	v_mul_f32_e32 v208, v116, v217
	v_mul_f32_e32 v209, v100, v217
	s_waitcnt vmcnt(11)
	v_mul_f32_e32 v206, v209, v137
	v_mul_f32_e32 v207, v208, v137
	v_fma_f32 v206, v208, v136, -v206
	v_fma_f32 v207, v209, v136, v207
	v_cvt_pk_bf16_f32 v206, v206, v207
	ds_write_b16 v201, v206 offset:1152
	ds_write_b16_d16_hi v201, v206 offset:1216
	v_mul_f32_e32 v208, v117, v218
	v_mul_f32_e32 v209, v101, v218
	s_waitcnt vmcnt(10)
	v_mul_f32_e32 v206, v209, v139
	v_mul_f32_e32 v207, v208, v139
	v_fma_f32 v206, v208, v138, -v206
	v_fma_f32 v207, v209, v138, v207
	v_cvt_pk_bf16_f32 v206, v206, v207
	ds_write_b16 v201, v206 offset:1296
	ds_write_b16_d16_hi v201, v206 offset:1360
	v_mul_f32_e32 v208, v118, v219
	v_mul_f32_e32 v209, v102, v219
	s_waitcnt vmcnt(9)
	v_mul_f32_e32 v206, v209, v141
	v_mul_f32_e32 v207, v208, v141
	v_fma_f32 v206, v208, v140, -v206
	v_fma_f32 v207, v209, v140, v207
	v_cvt_pk_bf16_f32 v206, v206, v207
	ds_write_b16 v201, v206 offset:1440
	ds_write_b16_d16_hi v201, v206 offset:1504
	v_mul_f32_e32 v208, v119, v220
	v_mul_f32_e32 v209, v103, v220
	s_waitcnt vmcnt(8)
	v_mul_f32_e32 v206, v209, v143
	v_mul_f32_e32 v207, v208, v143
	v_fma_f32 v206, v208, v142, -v206
	v_fma_f32 v207, v209, v142, v207
	v_cvt_pk_bf16_f32 v206, v206, v207
	ds_write_b16 v201, v206 offset:1584
	ds_write_b16_d16_hi v201, v206 offset:1648
	v_mul_f32_e32 v208, v120, v221
	v_mul_f32_e32 v209, v104, v221
	s_waitcnt vmcnt(7)
	v_mul_f32_e32 v206, v209, v145
	v_mul_f32_e32 v207, v208, v145
	v_fma_f32 v206, v208, v144, -v206
	v_fma_f32 v207, v209, v144, v207
	v_cvt_pk_bf16_f32 v206, v206, v207
	ds_write_b16 v201, v206 offset:2304
	ds_write_b16_d16_hi v201, v206 offset:2368
	v_mul_f32_e32 v208, v121, v222
	v_mul_f32_e32 v209, v105, v222
	s_waitcnt vmcnt(6)
	v_mul_f32_e32 v206, v209, v147
	v_mul_f32_e32 v207, v208, v147
	v_fma_f32 v206, v208, v146, -v206
	v_fma_f32 v207, v209, v146, v207
	v_cvt_pk_bf16_f32 v206, v206, v207
	ds_write_b16 v201, v206 offset:2448
	ds_write_b16_d16_hi v201, v206 offset:2512
	v_mul_f32_e32 v208, v122, v223
	v_mul_f32_e32 v209, v106, v223
	s_waitcnt vmcnt(5)
	v_mul_f32_e32 v206, v209, v149
	v_mul_f32_e32 v207, v208, v149
	v_fma_f32 v206, v208, v148, -v206
	v_fma_f32 v207, v209, v148, v207
	v_cvt_pk_bf16_f32 v206, v206, v207
	ds_write_b16 v201, v206 offset:2592
	ds_write_b16_d16_hi v201, v206 offset:2656
	v_mul_f32_e32 v208, v123, v224
	v_mul_f32_e32 v209, v107, v224
	s_waitcnt vmcnt(4)
	v_mul_f32_e32 v206, v209, v151
	v_mul_f32_e32 v207, v208, v151
	v_fma_f32 v206, v208, v150, -v206
	v_fma_f32 v207, v209, v150, v207
	v_cvt_pk_bf16_f32 v206, v206, v207
	ds_write_b16 v201, v206 offset:2736
	ds_write_b16_d16_hi v201, v206 offset:2800
	v_mul_f32_e32 v208, v124, v225
	v_mul_f32_e32 v209, v108, v225
	s_waitcnt vmcnt(3)
	v_mul_f32_e32 v206, v209, v153
	v_mul_f32_e32 v207, v208, v153
	v_fma_f32 v206, v208, v152, -v206
	v_fma_f32 v207, v209, v152, v207
	v_cvt_pk_bf16_f32 v206, v206, v207
	ds_write_b16 v201, v206 offset:3456
	ds_write_b16_d16_hi v201, v206 offset:3520
	v_mul_f32_e32 v208, v125, v226
	v_mul_f32_e32 v209, v109, v226
	s_waitcnt vmcnt(2)
	v_mul_f32_e32 v206, v209, v155
	v_mul_f32_e32 v207, v208, v155
	v_fma_f32 v206, v208, v154, -v206
	v_fma_f32 v207, v209, v154, v207
	v_cvt_pk_bf16_f32 v206, v206, v207
	ds_write_b16 v201, v206 offset:3600
	ds_write_b16_d16_hi v201, v206 offset:3664
	v_mul_f32_e32 v208, v126, v227
	v_mul_f32_e32 v209, v110, v227
	s_waitcnt vmcnt(1)
	v_mul_f32_e32 v206, v209, v157
	v_mul_f32_e32 v207, v208, v157
	v_fma_f32 v206, v208, v156, -v206
	v_fma_f32 v207, v209, v156, v207
	v_cvt_pk_bf16_f32 v206, v206, v207
	ds_write_b16 v201, v206 offset:3744
	ds_write_b16_d16_hi v201, v206 offset:3808
	v_mul_f32_e32 v208, v127, v228
	v_mul_f32_e32 v209, v111, v228
	s_waitcnt vmcnt(0)
	v_mul_f32_e32 v206, v209, v159
	v_mul_f32_e32 v207, v208, v159
	v_fma_f32 v206, v208, v158, -v206
	v_fma_f32 v207, v209, v158, v207
	v_cvt_pk_bf16_f32 v206, v206, v207
	ds_write_b16 v201, v206 offset:3888
	ds_write_b16_d16_hi v201, v206 offset:3952
.Lmq3q_e00_st:
	v_mad_u32_u24 v211, v204, s99, v205
	s_lshl_b32 s99, s99, 3
	ds_read_b128 v[160:163], v202
	ds_read_b128 v[164:167], v202 offset:1152
	ds_read_b128 v[168:171], v202 offset:2304
	ds_read_b128 v[172:175], v202 offset:3456
	v_add_u32_e32 v206, s89, v211
	s_add_u32 s89, s89, s99
	v_add_u32_e32 v207, s89, v211
	s_add_u32 s89, s89, s99
	v_add_u32_e32 v208, s89, v211
	s_add_u32 s89, s89, s99
	v_add_u32_e32 v209, s89, v211
	s_waitcnt lgkmcnt(3)
	global_store_dwordx4 v206, v[160:163], s[2:3]
	s_waitcnt lgkmcnt(2)
	global_store_dwordx4 v207, v[164:167], s[2:3]
	s_waitcnt lgkmcnt(1)
	global_store_dwordx4 v208, v[168:171], s[2:3]
	s_waitcnt lgkmcnt(0)
	global_store_dwordx4 v209, v[172:175], s[2:3]
	s_add_u32 s94, s92, 0
	s_add_u32 s95, s93, 64
	s_lshr_b32 s90, s95, 6
	s_lshr_b32 s96, s94, 12
	s_and_b32 s97, s94, 0xfff
	s_mul_i32 s91, s90, 11
	s_lshr_b32 s91, s91, 5
	s_mul_i32 s98, s91, 3
	s_sub_u32 s98, s90, s98
	s_mul_i32 s89, s96, 0xc00000
	s_mul_i32 s91, s91, 0x180000
	s_add_u32 s89, s89, s91
	s_lshl_b32 s91, s98, 7
	s_add_u32 s89, s89, s91
	s_mul_i32 s91, s97, 0x180
	s_add_u32 s89, s89, s91
	s_movk_i32 s99, 0x180
	s_mov_b64 s[2:3], s[12:13]
	s_cmp_eq_u32 s98, 2
	s_cbranch_scc1 .Lmq3q_e01_rope
.Lmq3q_e01_plain:
	v_mul_f32_e32 v206, v80, v213
	v_mul_f32_e32 v207, v64, v213
	v_cvt_pk_bf16_f32 v206, v206, v207
	ds_write_b16 v201, v206
	ds_write_b16_d16_hi v201, v206 offset:64
	v_mul_f32_e32 v208, v81, v214
	v_mul_f32_e32 v209, v65, v214
	v_cvt_pk_bf16_f32 v208, v208, v209
	ds_write_b16 v201, v208 offset:144
	ds_write_b16_d16_hi v201, v208 offset:208
	v_mul_f32_e32 v206, v82, v215
	v_mul_f32_e32 v207, v66, v215
	v_cvt_pk_bf16_f32 v206, v206, v207
	ds_write_b16 v201, v206 offset:288
	ds_write_b16_d16_hi v201, v206 offset:352
	v_mul_f32_e32 v208, v83, v216
	v_mul_f32_e32 v209, v67, v216
	v_cvt_pk_bf16_f32 v208, v208, v209
	ds_write_b16 v201, v208 offset:432
	ds_write_b16_d16_hi v201, v208 offset:496
	v_mul_f32_e32 v206, v84, v217
	v_mul_f32_e32 v207, v68, v217
	v_cvt_pk_bf16_f32 v206, v206, v207
	ds_write_b16 v201, v206 offset:1152
	ds_write_b16_d16_hi v201, v206 offset:1216
	v_mul_f32_e32 v208, v85, v218
	v_mul_f32_e32 v209, v69, v218
	v_cvt_pk_bf16_f32 v208, v208, v209
	ds_write_b16 v201, v208 offset:1296
	ds_write_b16_d16_hi v201, v208 offset:1360
	v_mul_f32_e32 v206, v86, v219
	v_mul_f32_e32 v207, v70, v219
	v_cvt_pk_bf16_f32 v206, v206, v207
	ds_write_b16 v201, v206 offset:1440
	ds_write_b16_d16_hi v201, v206 offset:1504
	v_mul_f32_e32 v208, v87, v220
	v_mul_f32_e32 v209, v71, v220
	v_cvt_pk_bf16_f32 v208, v208, v209
	ds_write_b16 v201, v208 offset:1584
	ds_write_b16_d16_hi v201, v208 offset:1648
	v_mul_f32_e32 v206, v88, v221
	v_mul_f32_e32 v207, v72, v221
	v_cvt_pk_bf16_f32 v206, v206, v207
	ds_write_b16 v201, v206 offset:2304
	ds_write_b16_d16_hi v201, v206 offset:2368
	v_mul_f32_e32 v208, v89, v222
	v_mul_f32_e32 v209, v73, v222
	v_cvt_pk_bf16_f32 v208, v208, v209
	ds_write_b16 v201, v208 offset:2448
	ds_write_b16_d16_hi v201, v208 offset:2512
	v_mul_f32_e32 v206, v90, v223
	v_mul_f32_e32 v207, v74, v223
	v_cvt_pk_bf16_f32 v206, v206, v207
	ds_write_b16 v201, v206 offset:2592
	ds_write_b16_d16_hi v201, v206 offset:2656
	v_mul_f32_e32 v208, v91, v224
	v_mul_f32_e32 v209, v75, v224
	v_cvt_pk_bf16_f32 v208, v208, v209
	ds_write_b16 v201, v208 offset:2736
	ds_write_b16_d16_hi v201, v208 offset:2800
	v_mul_f32_e32 v206, v92, v225
	v_mul_f32_e32 v207, v76, v225
	v_cvt_pk_bf16_f32 v206, v206, v207
	ds_write_b16 v201, v206 offset:3456
	ds_write_b16_d16_hi v201, v206 offset:3520
	v_mul_f32_e32 v208, v93, v226
	v_mul_f32_e32 v209, v77, v226
	v_cvt_pk_bf16_f32 v208, v208, v209
	ds_write_b16 v201, v208 offset:3600
	ds_write_b16_d16_hi v201, v208 offset:3664
	v_mul_f32_e32 v206, v94, v227
	v_mul_f32_e32 v207, v78, v227
	v_cvt_pk_bf16_f32 v206, v206, v207
	ds_write_b16 v201, v206 offset:3744
	ds_write_b16_d16_hi v201, v206 offset:3808
	v_mul_f32_e32 v208, v95, v228
	v_mul_f32_e32 v209, v79, v228
	v_cvt_pk_bf16_f32 v208, v208, v209
	ds_write_b16 v201, v208 offset:3888
	ds_write_b16_d16_hi v201, v208 offset:3952
	s_branch .Lmq3q_e01_st
.Lmq3q_e01_rope:
	v_add_u32_e32 v206, s94, v203
	v_lshlrev_b32_e32 v206, 8, v206
	v_add_u32_e32 v176, v206, v200
	v_mov_b32_e32 v177, 0
	v_lshl_add_u64 v[176:177], s[10:11], 0, v[176:177]
	global_load_dwordx2 v[128:129], v[176:177], off
	global_load_dwordx2 v[130:131], v[176:177], off offset:256
	global_load_dwordx2 v[132:133], v[176:177], off offset:512
	global_load_dwordx2 v[134:135], v[176:177], off offset:768
	global_load_dwordx2 v[136:137], v[176:177], off offset:2048
	global_load_dwordx2 v[138:139], v[176:177], off offset:2304
	global_load_dwordx2 v[140:141], v[176:177], off offset:2560
	global_load_dwordx2 v[142:143], v[176:177], off offset:2816
	v_add_co_u32_e32 v178, vcc, 0x1000, v176
	s_nop 1
	v_addc_co_u32_e32 v179, vcc, 0, v177, vcc
	global_load_dwordx2 v[144:145], v[178:179], off
	global_load_dwordx2 v[146:147], v[178:179], off offset:256
	global_load_dwordx2 v[148:149], v[178:179], off offset:512
	global_load_dwordx2 v[150:151], v[178:179], off offset:768
	global_load_dwordx2 v[152:153], v[178:179], off offset:2048
	global_load_dwordx2 v[154:155], v[178:179], off offset:2304
	global_load_dwordx2 v[156:157], v[178:179], off offset:2560
	global_load_dwordx2 v[158:159], v[178:179], off offset:2816
	v_mul_f32_e32 v208, v80, v213
	v_mul_f32_e32 v209, v64, v213
	s_waitcnt vmcnt(15)
	v_mul_f32_e32 v206, v209, v129
	v_mul_f32_e32 v207, v208, v129
	v_fma_f32 v206, v208, v128, -v206
	v_fma_f32 v207, v209, v128, v207
	v_cvt_pk_bf16_f32 v206, v206, v207
	ds_write_b16 v201, v206
	ds_write_b16_d16_hi v201, v206 offset:64
	v_mul_f32_e32 v208, v81, v214
	v_mul_f32_e32 v209, v65, v214
	s_waitcnt vmcnt(14)
	v_mul_f32_e32 v206, v209, v131
	v_mul_f32_e32 v207, v208, v131
	v_fma_f32 v206, v208, v130, -v206
	v_fma_f32 v207, v209, v130, v207
	v_cvt_pk_bf16_f32 v206, v206, v207
	ds_write_b16 v201, v206 offset:144
	ds_write_b16_d16_hi v201, v206 offset:208
	v_mul_f32_e32 v208, v82, v215
	v_mul_f32_e32 v209, v66, v215
	s_waitcnt vmcnt(13)
	v_mul_f32_e32 v206, v209, v133
	v_mul_f32_e32 v207, v208, v133
	v_fma_f32 v206, v208, v132, -v206
	v_fma_f32 v207, v209, v132, v207
	v_cvt_pk_bf16_f32 v206, v206, v207
	ds_write_b16 v201, v206 offset:288
	ds_write_b16_d16_hi v201, v206 offset:352
	v_mul_f32_e32 v208, v83, v216
	v_mul_f32_e32 v209, v67, v216
	s_waitcnt vmcnt(12)
	v_mul_f32_e32 v206, v209, v135
	v_mul_f32_e32 v207, v208, v135
	v_fma_f32 v206, v208, v134, -v206
	v_fma_f32 v207, v209, v134, v207
	v_cvt_pk_bf16_f32 v206, v206, v207
	ds_write_b16 v201, v206 offset:432
	ds_write_b16_d16_hi v201, v206 offset:496
	v_mul_f32_e32 v208, v84, v217
	v_mul_f32_e32 v209, v68, v217
	s_waitcnt vmcnt(11)
	v_mul_f32_e32 v206, v209, v137
	v_mul_f32_e32 v207, v208, v137
	v_fma_f32 v206, v208, v136, -v206
	v_fma_f32 v207, v209, v136, v207
	v_cvt_pk_bf16_f32 v206, v206, v207
	ds_write_b16 v201, v206 offset:1152
	ds_write_b16_d16_hi v201, v206 offset:1216
	v_mul_f32_e32 v208, v85, v218
	v_mul_f32_e32 v209, v69, v218
	s_waitcnt vmcnt(10)
	v_mul_f32_e32 v206, v209, v139
	v_mul_f32_e32 v207, v208, v139
	v_fma_f32 v206, v208, v138, -v206
	v_fma_f32 v207, v209, v138, v207
	v_cvt_pk_bf16_f32 v206, v206, v207
	ds_write_b16 v201, v206 offset:1296
	ds_write_b16_d16_hi v201, v206 offset:1360
	v_mul_f32_e32 v208, v86, v219
	v_mul_f32_e32 v209, v70, v219
	s_waitcnt vmcnt(9)
	v_mul_f32_e32 v206, v209, v141
	v_mul_f32_e32 v207, v208, v141
	v_fma_f32 v206, v208, v140, -v206
	v_fma_f32 v207, v209, v140, v207
	v_cvt_pk_bf16_f32 v206, v206, v207
	ds_write_b16 v201, v206 offset:1440
	ds_write_b16_d16_hi v201, v206 offset:1504
	v_mul_f32_e32 v208, v87, v220
	v_mul_f32_e32 v209, v71, v220
	s_waitcnt vmcnt(8)
	v_mul_f32_e32 v206, v209, v143
	v_mul_f32_e32 v207, v208, v143
	v_fma_f32 v206, v208, v142, -v206
	v_fma_f32 v207, v209, v142, v207
	v_cvt_pk_bf16_f32 v206, v206, v207
	ds_write_b16 v201, v206 offset:1584
	ds_write_b16_d16_hi v201, v206 offset:1648
	v_mul_f32_e32 v208, v88, v221
	v_mul_f32_e32 v209, v72, v221
	s_waitcnt vmcnt(7)
	v_mul_f32_e32 v206, v209, v145
	v_mul_f32_e32 v207, v208, v145
	v_fma_f32 v206, v208, v144, -v206
	v_fma_f32 v207, v209, v144, v207
	v_cvt_pk_bf16_f32 v206, v206, v207
	ds_write_b16 v201, v206 offset:2304
	ds_write_b16_d16_hi v201, v206 offset:2368
	v_mul_f32_e32 v208, v89, v222
	v_mul_f32_e32 v209, v73, v222
	s_waitcnt vmcnt(6)
	v_mul_f32_e32 v206, v209, v147
	v_mul_f32_e32 v207, v208, v147
	v_fma_f32 v206, v208, v146, -v206
	v_fma_f32 v207, v209, v146, v207
	v_cvt_pk_bf16_f32 v206, v206, v207
	ds_write_b16 v201, v206 offset:2448
	ds_write_b16_d16_hi v201, v206 offset:2512
	v_mul_f32_e32 v208, v90, v223
	v_mul_f32_e32 v209, v74, v223
	s_waitcnt vmcnt(5)
	v_mul_f32_e32 v206, v209, v149
	v_mul_f32_e32 v207, v208, v149
	v_fma_f32 v206, v208, v148, -v206
	v_fma_f32 v207, v209, v148, v207
	v_cvt_pk_bf16_f32 v206, v206, v207
	ds_write_b16 v201, v206 offset:2592
	ds_write_b16_d16_hi v201, v206 offset:2656
	v_mul_f32_e32 v208, v91, v224
	v_mul_f32_e32 v209, v75, v224
	s_waitcnt vmcnt(4)
	v_mul_f32_e32 v206, v209, v151
	v_mul_f32_e32 v207, v208, v151
	v_fma_f32 v206, v208, v150, -v206
	v_fma_f32 v207, v209, v150, v207
	v_cvt_pk_bf16_f32 v206, v206, v207
	ds_write_b16 v201, v206 offset:2736
	ds_write_b16_d16_hi v201, v206 offset:2800
	v_mul_f32_e32 v208, v92, v225
	v_mul_f32_e32 v209, v76, v225
	s_waitcnt vmcnt(3)
	v_mul_f32_e32 v206, v209, v153
	v_mul_f32_e32 v207, v208, v153
	v_fma_f32 v206, v208, v152, -v206
	v_fma_f32 v207, v209, v152, v207
	v_cvt_pk_bf16_f32 v206, v206, v207
	ds_write_b16 v201, v206 offset:3456
	ds_write_b16_d16_hi v201, v206 offset:3520
	v_mul_f32_e32 v208, v93, v226
	v_mul_f32_e32 v209, v77, v226
	s_waitcnt vmcnt(2)
	v_mul_f32_e32 v206, v209, v155
	v_mul_f32_e32 v207, v208, v155
	v_fma_f32 v206, v208, v154, -v206
	v_fma_f32 v207, v209, v154, v207
	v_cvt_pk_bf16_f32 v206, v206, v207
	ds_write_b16 v201, v206 offset:3600
	ds_write_b16_d16_hi v201, v206 offset:3664
	v_mul_f32_e32 v208, v94, v227
	v_mul_f32_e32 v209, v78, v227
	s_waitcnt vmcnt(1)
	v_mul_f32_e32 v206, v209, v157
	v_mul_f32_e32 v207, v208, v157
	v_fma_f32 v206, v208, v156, -v206
	v_fma_f32 v207, v209, v156, v207
	v_cvt_pk_bf16_f32 v206, v206, v207
	ds_write_b16 v201, v206 offset:3744
	ds_write_b16_d16_hi v201, v206 offset:3808
	v_mul_f32_e32 v208, v95, v228
	v_mul_f32_e32 v209, v79, v228
	s_waitcnt vmcnt(0)
	v_mul_f32_e32 v206, v209, v159
	v_mul_f32_e32 v207, v208, v159
	v_fma_f32 v206, v208, v158, -v206
	v_fma_f32 v207, v209, v158, v207
	v_cvt_pk_bf16_f32 v206, v206, v207
	ds_write_b16 v201, v206 offset:3888
	ds_write_b16_d16_hi v201, v206 offset:3952
.Lmq3q_e01_st:
	v_mad_u32_u24 v211, v204, s99, v205
	s_lshl_b32 s99, s99, 3
	ds_read_b128 v[160:163], v202
	ds_read_b128 v[164:167], v202 offset:1152
	ds_read_b128 v[168:171], v202 offset:2304
	ds_read_b128 v[172:175], v202 offset:3456
	v_add_u32_e32 v206, s89, v211
	s_add_u32 s89, s89, s99
	v_add_u32_e32 v207, s89, v211
	s_add_u32 s89, s89, s99
	v_add_u32_e32 v208, s89, v211
	s_add_u32 s89, s89, s99
	v_add_u32_e32 v209, s89, v211
	s_waitcnt lgkmcnt(3)
	global_store_dwordx4 v206, v[160:163], s[2:3]
	s_waitcnt lgkmcnt(2)
	global_store_dwordx4 v207, v[164:167], s[2:3]
	s_waitcnt lgkmcnt(1)
	global_store_dwordx4 v208, v[168:171], s[2:3]
	s_waitcnt lgkmcnt(0)
	global_store_dwordx4 v209, v[172:175], s[2:3]
	s_add_u32 s94, s92, 32
	s_add_u32 s95, s93, 0
	s_lshr_b32 s90, s95, 6
	s_lshr_b32 s96, s94, 12
	s_and_b32 s97, s94, 0xfff
	s_mul_i32 s91, s90, 11
	s_lshr_b32 s91, s91, 5
	s_mul_i32 s98, s91, 3
	s_sub_u32 s98, s90, s98
	s_mul_i32 s89, s96, 0xc00000
	s_mul_i32 s91, s91, 0x180000
	s_add_u32 s89, s89, s91
	s_lshl_b32 s91, s98, 7
	s_add_u32 s89, s89, s91
	s_mul_i32 s91, s97, 0x180
	s_add_u32 s89, s89, s91
	s_movk_i32 s99, 0x180
	s_mov_b64 s[2:3], s[12:13]
	s_cmp_eq_u32 s98, 2
	s_cbranch_scc1 .Lmq3q_e10_rope
.Lmq3q_e10_plain:
	v_mul_f32_e32 v206, v48, v229
	v_mul_f32_e32 v207, v32, v229
	v_cvt_pk_bf16_f32 v206, v206, v207
	ds_write_b16 v201, v206
	ds_write_b16_d16_hi v201, v206 offset:64
	v_mul_f32_e32 v208, v49, v230
	v_mul_f32_e32 v209, v33, v230
	v_cvt_pk_bf16_f32 v208, v208, v209
	ds_write_b16 v201, v208 offset:144
	ds_write_b16_d16_hi v201, v208 offset:208
	v_mul_f32_e32 v206, v50, v231
	v_mul_f32_e32 v207, v34, v231
	v_cvt_pk_bf16_f32 v206, v206, v207
	ds_write_b16 v201, v206 offset:288
	ds_write_b16_d16_hi v201, v206 offset:352
	v_mul_f32_e32 v208, v51, v232
	v_mul_f32_e32 v209, v35, v232
	v_cvt_pk_bf16_f32 v208, v208, v209
	ds_write_b16 v201, v208 offset:432
	ds_write_b16_d16_hi v201, v208 offset:496
	v_mul_f32_e32 v206, v52, v233
	v_mul_f32_e32 v207, v36, v233
	v_cvt_pk_bf16_f32 v206, v206, v207
	ds_write_b16 v201, v206 offset:1152
	ds_write_b16_d16_hi v201, v206 offset:1216
	v_mul_f32_e32 v208, v53, v234
	v_mul_f32_e32 v209, v37, v234
	v_cvt_pk_bf16_f32 v208, v208, v209
	ds_write_b16 v201, v208 offset:1296
	ds_write_b16_d16_hi v201, v208 offset:1360
	v_mul_f32_e32 v206, v54, v235
	v_mul_f32_e32 v207, v38, v235
	v_cvt_pk_bf16_f32 v206, v206, v207
	ds_write_b16 v201, v206 offset:1440
	ds_write_b16_d16_hi v201, v206 offset:1504
	v_mul_f32_e32 v208, v55, v236
	v_mul_f32_e32 v209, v39, v236
	v_cvt_pk_bf16_f32 v208, v208, v209
	ds_write_b16 v201, v208 offset:1584
	ds_write_b16_d16_hi v201, v208 offset:1648
	v_mul_f32_e32 v206, v56, v237
	v_mul_f32_e32 v207, v40, v237
	v_cvt_pk_bf16_f32 v206, v206, v207
	ds_write_b16 v201, v206 offset:2304
	ds_write_b16_d16_hi v201, v206 offset:2368
	v_mul_f32_e32 v208, v57, v238
	v_mul_f32_e32 v209, v41, v238
	v_cvt_pk_bf16_f32 v208, v208, v209
	ds_write_b16 v201, v208 offset:2448
	ds_write_b16_d16_hi v201, v208 offset:2512
	v_mul_f32_e32 v206, v58, v239
	v_mul_f32_e32 v207, v42, v239
	v_cvt_pk_bf16_f32 v206, v206, v207
	ds_write_b16 v201, v206 offset:2592
	ds_write_b16_d16_hi v201, v206 offset:2656
	v_mul_f32_e32 v208, v59, v240
	v_mul_f32_e32 v209, v43, v240
	v_cvt_pk_bf16_f32 v208, v208, v209
	ds_write_b16 v201, v208 offset:2736
	ds_write_b16_d16_hi v201, v208 offset:2800
	v_mul_f32_e32 v206, v60, v241
	v_mul_f32_e32 v207, v44, v241
	v_cvt_pk_bf16_f32 v206, v206, v207
	ds_write_b16 v201, v206 offset:3456
	ds_write_b16_d16_hi v201, v206 offset:3520
	v_mul_f32_e32 v208, v61, v242
	v_mul_f32_e32 v209, v45, v242
	v_cvt_pk_bf16_f32 v208, v208, v209
	ds_write_b16 v201, v208 offset:3600
	ds_write_b16_d16_hi v201, v208 offset:3664
	v_mul_f32_e32 v206, v62, v243
	v_mul_f32_e32 v207, v46, v243
	v_cvt_pk_bf16_f32 v206, v206, v207
	ds_write_b16 v201, v206 offset:3744
	ds_write_b16_d16_hi v201, v206 offset:3808
	v_mul_f32_e32 v208, v63, v244
	v_mul_f32_e32 v209, v47, v244
	v_cvt_pk_bf16_f32 v208, v208, v209
	ds_write_b16 v201, v208 offset:3888
	ds_write_b16_d16_hi v201, v208 offset:3952
	s_branch .Lmq3q_e10_st
.Lmq3q_e10_rope:
	v_add_u32_e32 v206, s94, v203
	v_lshlrev_b32_e32 v206, 8, v206
	v_add_u32_e32 v176, v206, v200
	v_mov_b32_e32 v177, 0
	v_lshl_add_u64 v[176:177], s[10:11], 0, v[176:177]
	global_load_dwordx2 v[128:129], v[176:177], off
	global_load_dwordx2 v[130:131], v[176:177], off offset:256
	global_load_dwordx2 v[132:133], v[176:177], off offset:512
	global_load_dwordx2 v[134:135], v[176:177], off offset:768
	global_load_dwordx2 v[136:137], v[176:177], off offset:2048
	global_load_dwordx2 v[138:139], v[176:177], off offset:2304
	global_load_dwordx2 v[140:141], v[176:177], off offset:2560
	global_load_dwordx2 v[142:143], v[176:177], off offset:2816
	v_add_co_u32_e32 v178, vcc, 0x1000, v176
	s_nop 1
	v_addc_co_u32_e32 v179, vcc, 0, v177, vcc
	global_load_dwordx2 v[144:145], v[178:179], off
	global_load_dwordx2 v[146:147], v[178:179], off offset:256
	global_load_dwordx2 v[148:149], v[178:179], off offset:512
	global_load_dwordx2 v[150:151], v[178:179], off offset:768
	global_load_dwordx2 v[152:153], v[178:179], off offset:2048
	global_load_dwordx2 v[154:155], v[178:179], off offset:2304
	global_load_dwordx2 v[156:157], v[178:179], off offset:2560
	global_load_dwordx2 v[158:159], v[178:179], off offset:2816
	v_mul_f32_e32 v208, v48, v229
	v_mul_f32_e32 v209, v32, v229
	s_waitcnt vmcnt(15)
	v_mul_f32_e32 v206, v209, v129
	v_mul_f32_e32 v207, v208, v129
	v_fma_f32 v206, v208, v128, -v206
	v_fma_f32 v207, v209, v128, v207
	v_cvt_pk_bf16_f32 v206, v206, v207
	ds_write_b16 v201, v206
	ds_write_b16_d16_hi v201, v206 offset:64
	v_mul_f32_e32 v208, v49, v230
	v_mul_f32_e32 v209, v33, v230
	s_waitcnt vmcnt(14)
	v_mul_f32_e32 v206, v209, v131
	v_mul_f32_e32 v207, v208, v131
	v_fma_f32 v206, v208, v130, -v206
	v_fma_f32 v207, v209, v130, v207
	v_cvt_pk_bf16_f32 v206, v206, v207
	ds_write_b16 v201, v206 offset:144
	ds_write_b16_d16_hi v201, v206 offset:208
	v_mul_f32_e32 v208, v50, v231
	v_mul_f32_e32 v209, v34, v231
	s_waitcnt vmcnt(13)
	v_mul_f32_e32 v206, v209, v133
	v_mul_f32_e32 v207, v208, v133
	v_fma_f32 v206, v208, v132, -v206
	v_fma_f32 v207, v209, v132, v207
	v_cvt_pk_bf16_f32 v206, v206, v207
	ds_write_b16 v201, v206 offset:288
	ds_write_b16_d16_hi v201, v206 offset:352
	v_mul_f32_e32 v208, v51, v232
	v_mul_f32_e32 v209, v35, v232
	s_waitcnt vmcnt(12)
	v_mul_f32_e32 v206, v209, v135
	v_mul_f32_e32 v207, v208, v135
	v_fma_f32 v206, v208, v134, -v206
	v_fma_f32 v207, v209, v134, v207
	v_cvt_pk_bf16_f32 v206, v206, v207
	ds_write_b16 v201, v206 offset:432
	ds_write_b16_d16_hi v201, v206 offset:496
	v_mul_f32_e32 v208, v52, v233
	v_mul_f32_e32 v209, v36, v233
	s_waitcnt vmcnt(11)
	v_mul_f32_e32 v206, v209, v137
	v_mul_f32_e32 v207, v208, v137
	v_fma_f32 v206, v208, v136, -v206
	v_fma_f32 v207, v209, v136, v207
	v_cvt_pk_bf16_f32 v206, v206, v207
	ds_write_b16 v201, v206 offset:1152
	ds_write_b16_d16_hi v201, v206 offset:1216
	v_mul_f32_e32 v208, v53, v234
	v_mul_f32_e32 v209, v37, v234
	s_waitcnt vmcnt(10)
	v_mul_f32_e32 v206, v209, v139
	v_mul_f32_e32 v207, v208, v139
	v_fma_f32 v206, v208, v138, -v206
	v_fma_f32 v207, v209, v138, v207
	v_cvt_pk_bf16_f32 v206, v206, v207
	ds_write_b16 v201, v206 offset:1296
	ds_write_b16_d16_hi v201, v206 offset:1360
	v_mul_f32_e32 v208, v54, v235
	v_mul_f32_e32 v209, v38, v235
	s_waitcnt vmcnt(9)
	v_mul_f32_e32 v206, v209, v141
	v_mul_f32_e32 v207, v208, v141
	v_fma_f32 v206, v208, v140, -v206
	v_fma_f32 v207, v209, v140, v207
	v_cvt_pk_bf16_f32 v206, v206, v207
	ds_write_b16 v201, v206 offset:1440
	ds_write_b16_d16_hi v201, v206 offset:1504
	v_mul_f32_e32 v208, v55, v236
	v_mul_f32_e32 v209, v39, v236
	s_waitcnt vmcnt(8)
	v_mul_f32_e32 v206, v209, v143
	v_mul_f32_e32 v207, v208, v143
	v_fma_f32 v206, v208, v142, -v206
	v_fma_f32 v207, v209, v142, v207
	v_cvt_pk_bf16_f32 v206, v206, v207
	ds_write_b16 v201, v206 offset:1584
	ds_write_b16_d16_hi v201, v206 offset:1648
	v_mul_f32_e32 v208, v56, v237
	v_mul_f32_e32 v209, v40, v237
	s_waitcnt vmcnt(7)
	v_mul_f32_e32 v206, v209, v145
	v_mul_f32_e32 v207, v208, v145
	v_fma_f32 v206, v208, v144, -v206
	v_fma_f32 v207, v209, v144, v207
	v_cvt_pk_bf16_f32 v206, v206, v207
	ds_write_b16 v201, v206 offset:2304
	ds_write_b16_d16_hi v201, v206 offset:2368
	v_mul_f32_e32 v208, v57, v238
	v_mul_f32_e32 v209, v41, v238
	s_waitcnt vmcnt(6)
	v_mul_f32_e32 v206, v209, v147
	v_mul_f32_e32 v207, v208, v147
	v_fma_f32 v206, v208, v146, -v206
	v_fma_f32 v207, v209, v146, v207
	v_cvt_pk_bf16_f32 v206, v206, v207
	ds_write_b16 v201, v206 offset:2448
	ds_write_b16_d16_hi v201, v206 offset:2512
	v_mul_f32_e32 v208, v58, v239
	v_mul_f32_e32 v209, v42, v239
	s_waitcnt vmcnt(5)
	v_mul_f32_e32 v206, v209, v149
	v_mul_f32_e32 v207, v208, v149
	v_fma_f32 v206, v208, v148, -v206
	v_fma_f32 v207, v209, v148, v207
	v_cvt_pk_bf16_f32 v206, v206, v207
	ds_write_b16 v201, v206 offset:2592
	ds_write_b16_d16_hi v201, v206 offset:2656
	v_mul_f32_e32 v208, v59, v240
	v_mul_f32_e32 v209, v43, v240
	s_waitcnt vmcnt(4)
	v_mul_f32_e32 v206, v209, v151
	v_mul_f32_e32 v207, v208, v151
	v_fma_f32 v206, v208, v150, -v206
	v_fma_f32 v207, v209, v150, v207
	v_cvt_pk_bf16_f32 v206, v206, v207
	ds_write_b16 v201, v206 offset:2736
	ds_write_b16_d16_hi v201, v206 offset:2800
	v_mul_f32_e32 v208, v60, v241
	v_mul_f32_e32 v209, v44, v241
	s_waitcnt vmcnt(3)
	v_mul_f32_e32 v206, v209, v153
	v_mul_f32_e32 v207, v208, v153
	v_fma_f32 v206, v208, v152, -v206
	v_fma_f32 v207, v209, v152, v207
	v_cvt_pk_bf16_f32 v206, v206, v207
	ds_write_b16 v201, v206 offset:3456
	ds_write_b16_d16_hi v201, v206 offset:3520
	v_mul_f32_e32 v208, v61, v242
	v_mul_f32_e32 v209, v45, v242
	s_waitcnt vmcnt(2)
	v_mul_f32_e32 v206, v209, v155
	v_mul_f32_e32 v207, v208, v155
	v_fma_f32 v206, v208, v154, -v206
	v_fma_f32 v207, v209, v154, v207
	v_cvt_pk_bf16_f32 v206, v206, v207
	ds_write_b16 v201, v206 offset:3600
	ds_write_b16_d16_hi v201, v206 offset:3664
	v_mul_f32_e32 v208, v62, v243
	v_mul_f32_e32 v209, v46, v243
	s_waitcnt vmcnt(1)
	v_mul_f32_e32 v206, v209, v157
	v_mul_f32_e32 v207, v208, v157
	v_fma_f32 v206, v208, v156, -v206
	v_fma_f32 v207, v209, v156, v207
	v_cvt_pk_bf16_f32 v206, v206, v207
	ds_write_b16 v201, v206 offset:3744
	ds_write_b16_d16_hi v201, v206 offset:3808
	v_mul_f32_e32 v208, v63, v244
	v_mul_f32_e32 v209, v47, v244
	s_waitcnt vmcnt(0)
	v_mul_f32_e32 v206, v209, v159
	v_mul_f32_e32 v207, v208, v159
	v_fma_f32 v206, v208, v158, -v206
	v_fma_f32 v207, v209, v158, v207
	v_cvt_pk_bf16_f32 v206, v206, v207
	ds_write_b16 v201, v206 offset:3888
	ds_write_b16_d16_hi v201, v206 offset:3952
.Lmq3q_e10_st:
	v_mad_u32_u24 v211, v204, s99, v205
	s_lshl_b32 s99, s99, 3
	ds_read_b128 v[160:163], v202
	ds_read_b128 v[164:167], v202 offset:1152
	ds_read_b128 v[168:171], v202 offset:2304
	ds_read_b128 v[172:175], v202 offset:3456
	v_add_u32_e32 v206, s89, v211
	s_add_u32 s89, s89, s99
	v_add_u32_e32 v207, s89, v211
	s_add_u32 s89, s89, s99
	v_add_u32_e32 v208, s89, v211
	s_add_u32 s89, s89, s99
	v_add_u32_e32 v209, s89, v211
	s_waitcnt lgkmcnt(3)
	global_store_dwordx4 v206, v[160:163], s[2:3]
	s_waitcnt lgkmcnt(2)
	global_store_dwordx4 v207, v[164:167], s[2:3]
	s_waitcnt lgkmcnt(1)
	global_store_dwordx4 v208, v[168:171], s[2:3]
	s_waitcnt lgkmcnt(0)
	global_store_dwordx4 v209, v[172:175], s[2:3]
	s_add_u32 s94, s92, 32
	s_add_u32 s95, s93, 64
	s_lshr_b32 s90, s95, 6
	s_lshr_b32 s96, s94, 12
	s_and_b32 s97, s94, 0xfff
	s_mul_i32 s91, s90, 11
	s_lshr_b32 s91, s91, 5
	s_mul_i32 s98, s91, 3
	s_sub_u32 s98, s90, s98
	s_mul_i32 s89, s96, 0xc00000
	s_mul_i32 s91, s91, 0x180000
	s_add_u32 s89, s89, s91
	s_lshl_b32 s91, s98, 7
	s_add_u32 s89, s89, s91
	s_mul_i32 s91, s97, 0x180
	s_add_u32 s89, s89, s91
	s_movk_i32 s99, 0x180
	s_mov_b64 s[2:3], s[12:13]
	s_cmp_eq_u32 s98, 2
	s_cbranch_scc1 .Lmq3q_e11_rope
.Lmq3q_e11_plain:
	v_mul_f32_e32 v206, v16, v229
	v_mul_f32_e32 v207, v0, v229
	v_cvt_pk_bf16_f32 v206, v206, v207
	ds_write_b16 v201, v206
	ds_write_b16_d16_hi v201, v206 offset:64
	v_mul_f32_e32 v208, v17, v230
	v_mul_f32_e32 v209, v1, v230
	v_cvt_pk_bf16_f32 v208, v208, v209
	ds_write_b16 v201, v208 offset:144
	ds_write_b16_d16_hi v201, v208 offset:208
	v_mul_f32_e32 v206, v18, v231
	v_mul_f32_e32 v207, v2, v231
	v_cvt_pk_bf16_f32 v206, v206, v207
	ds_write_b16 v201, v206 offset:288
	ds_write_b16_d16_hi v201, v206 offset:352
	v_mul_f32_e32 v208, v19, v232
	v_mul_f32_e32 v209, v3, v232
	v_cvt_pk_bf16_f32 v208, v208, v209
	ds_write_b16 v201, v208 offset:432
	ds_write_b16_d16_hi v201, v208 offset:496
	v_mul_f32_e32 v206, v20, v233
	v_mul_f32_e32 v207, v4, v233
	v_cvt_pk_bf16_f32 v206, v206, v207
	ds_write_b16 v201, v206 offset:1152
	ds_write_b16_d16_hi v201, v206 offset:1216
	v_mul_f32_e32 v208, v21, v234
	v_mul_f32_e32 v209, v5, v234
	v_cvt_pk_bf16_f32 v208, v208, v209
	ds_write_b16 v201, v208 offset:1296
	ds_write_b16_d16_hi v201, v208 offset:1360
	v_mul_f32_e32 v206, v22, v235
	v_mul_f32_e32 v207, v6, v235
	v_cvt_pk_bf16_f32 v206, v206, v207
	ds_write_b16 v201, v206 offset:1440
	ds_write_b16_d16_hi v201, v206 offset:1504
	v_mul_f32_e32 v208, v23, v236
	v_mul_f32_e32 v209, v7, v236
	v_cvt_pk_bf16_f32 v208, v208, v209
	ds_write_b16 v201, v208 offset:1584
	ds_write_b16_d16_hi v201, v208 offset:1648
	v_mul_f32_e32 v206, v24, v237
	v_mul_f32_e32 v207, v8, v237
	v_cvt_pk_bf16_f32 v206, v206, v207
	ds_write_b16 v201, v206 offset:2304
	ds_write_b16_d16_hi v201, v206 offset:2368
	v_mul_f32_e32 v208, v25, v238
	v_mul_f32_e32 v209, v9, v238
	v_cvt_pk_bf16_f32 v208, v208, v209
	ds_write_b16 v201, v208 offset:2448
	ds_write_b16_d16_hi v201, v208 offset:2512
	v_mul_f32_e32 v206, v26, v239
	v_mul_f32_e32 v207, v10, v239
	v_cvt_pk_bf16_f32 v206, v206, v207
	ds_write_b16 v201, v206 offset:2592
	ds_write_b16_d16_hi v201, v206 offset:2656
	v_mul_f32_e32 v208, v27, v240
	v_mul_f32_e32 v209, v11, v240
	v_cvt_pk_bf16_f32 v208, v208, v209
	ds_write_b16 v201, v208 offset:2736
	ds_write_b16_d16_hi v201, v208 offset:2800
	v_mul_f32_e32 v206, v28, v241
	v_mul_f32_e32 v207, v12, v241
	v_cvt_pk_bf16_f32 v206, v206, v207
	ds_write_b16 v201, v206 offset:3456
	ds_write_b16_d16_hi v201, v206 offset:3520
	v_mul_f32_e32 v208, v29, v242
	v_mul_f32_e32 v209, v13, v242
	v_cvt_pk_bf16_f32 v208, v208, v209
	ds_write_b16 v201, v208 offset:3600
	ds_write_b16_d16_hi v201, v208 offset:3664
	v_mul_f32_e32 v206, v30, v243
	v_mul_f32_e32 v207, v14, v243
	v_cvt_pk_bf16_f32 v206, v206, v207
	ds_write_b16 v201, v206 offset:3744
	ds_write_b16_d16_hi v201, v206 offset:3808
	v_mul_f32_e32 v208, v31, v244
	v_mul_f32_e32 v209, v15, v244
	v_cvt_pk_bf16_f32 v208, v208, v209
	ds_write_b16 v201, v208 offset:3888
	ds_write_b16_d16_hi v201, v208 offset:3952
	s_branch .Lmq3q_e11_st
.Lmq3q_e11_rope:
	v_add_u32_e32 v206, s94, v203
	v_lshlrev_b32_e32 v206, 8, v206
	v_add_u32_e32 v176, v206, v200
	v_mov_b32_e32 v177, 0
	v_lshl_add_u64 v[176:177], s[10:11], 0, v[176:177]
	global_load_dwordx2 v[128:129], v[176:177], off
	global_load_dwordx2 v[130:131], v[176:177], off offset:256
	global_load_dwordx2 v[132:133], v[176:177], off offset:512
	global_load_dwordx2 v[134:135], v[176:177], off offset:768
	global_load_dwordx2 v[136:137], v[176:177], off offset:2048
	global_load_dwordx2 v[138:139], v[176:177], off offset:2304
	global_load_dwordx2 v[140:141], v[176:177], off offset:2560
	global_load_dwordx2 v[142:143], v[176:177], off offset:2816
	v_add_co_u32_e32 v178, vcc, 0x1000, v176
	s_nop 1
	v_addc_co_u32_e32 v179, vcc, 0, v177, vcc
	global_load_dwordx2 v[144:145], v[178:179], off
	global_load_dwordx2 v[146:147], v[178:179], off offset:256
	global_load_dwordx2 v[148:149], v[178:179], off offset:512
	global_load_dwordx2 v[150:151], v[178:179], off offset:768
	global_load_dwordx2 v[152:153], v[178:179], off offset:2048
	global_load_dwordx2 v[154:155], v[178:179], off offset:2304
	global_load_dwordx2 v[156:157], v[178:179], off offset:2560
	global_load_dwordx2 v[158:159], v[178:179], off offset:2816
	v_mul_f32_e32 v208, v16, v229
	v_mul_f32_e32 v209, v0, v229
	s_waitcnt vmcnt(15)
	v_mul_f32_e32 v206, v209, v129
	v_mul_f32_e32 v207, v208, v129
	v_fma_f32 v206, v208, v128, -v206
	v_fma_f32 v207, v209, v128, v207
	v_cvt_pk_bf16_f32 v206, v206, v207
	ds_write_b16 v201, v206
	ds_write_b16_d16_hi v201, v206 offset:64
	v_mul_f32_e32 v208, v17, v230
	v_mul_f32_e32 v209, v1, v230
	s_waitcnt vmcnt(14)
	v_mul_f32_e32 v206, v209, v131
	v_mul_f32_e32 v207, v208, v131
	v_fma_f32 v206, v208, v130, -v206
	v_fma_f32 v207, v209, v130, v207
	v_cvt_pk_bf16_f32 v206, v206, v207
	ds_write_b16 v201, v206 offset:144
	ds_write_b16_d16_hi v201, v206 offset:208
	v_mul_f32_e32 v208, v18, v231
	v_mul_f32_e32 v209, v2, v231
	s_waitcnt vmcnt(13)
	v_mul_f32_e32 v206, v209, v133
	v_mul_f32_e32 v207, v208, v133
	v_fma_f32 v206, v208, v132, -v206
	v_fma_f32 v207, v209, v132, v207
	v_cvt_pk_bf16_f32 v206, v206, v207
	ds_write_b16 v201, v206 offset:288
	ds_write_b16_d16_hi v201, v206 offset:352
	v_mul_f32_e32 v208, v19, v232
	v_mul_f32_e32 v209, v3, v232
	s_waitcnt vmcnt(12)
	v_mul_f32_e32 v206, v209, v135
	v_mul_f32_e32 v207, v208, v135
	v_fma_f32 v206, v208, v134, -v206
	v_fma_f32 v207, v209, v134, v207
	v_cvt_pk_bf16_f32 v206, v206, v207
	ds_write_b16 v201, v206 offset:432
	ds_write_b16_d16_hi v201, v206 offset:496
	v_mul_f32_e32 v208, v20, v233
	v_mul_f32_e32 v209, v4, v233
	s_waitcnt vmcnt(11)
	v_mul_f32_e32 v206, v209, v137
	v_mul_f32_e32 v207, v208, v137
	v_fma_f32 v206, v208, v136, -v206
	v_fma_f32 v207, v209, v136, v207
	v_cvt_pk_bf16_f32 v206, v206, v207
	ds_write_b16 v201, v206 offset:1152
	ds_write_b16_d16_hi v201, v206 offset:1216
	v_mul_f32_e32 v208, v21, v234
	v_mul_f32_e32 v209, v5, v234
	s_waitcnt vmcnt(10)
	v_mul_f32_e32 v206, v209, v139
	v_mul_f32_e32 v207, v208, v139
	v_fma_f32 v206, v208, v138, -v206
	v_fma_f32 v207, v209, v138, v207
	v_cvt_pk_bf16_f32 v206, v206, v207
	ds_write_b16 v201, v206 offset:1296
	ds_write_b16_d16_hi v201, v206 offset:1360
	v_mul_f32_e32 v208, v22, v235
	v_mul_f32_e32 v209, v6, v235
	s_waitcnt vmcnt(9)
	v_mul_f32_e32 v206, v209, v141
	v_mul_f32_e32 v207, v208, v141
	v_fma_f32 v206, v208, v140, -v206
	v_fma_f32 v207, v209, v140, v207
	v_cvt_pk_bf16_f32 v206, v206, v207
	ds_write_b16 v201, v206 offset:1440
	ds_write_b16_d16_hi v201, v206 offset:1504
	v_mul_f32_e32 v208, v23, v236
	v_mul_f32_e32 v209, v7, v236
	s_waitcnt vmcnt(8)
	v_mul_f32_e32 v206, v209, v143
	v_mul_f32_e32 v207, v208, v143
	v_fma_f32 v206, v208, v142, -v206
	v_fma_f32 v207, v209, v142, v207
	v_cvt_pk_bf16_f32 v206, v206, v207
	ds_write_b16 v201, v206 offset:1584
	ds_write_b16_d16_hi v201, v206 offset:1648
	v_mul_f32_e32 v208, v24, v237
	v_mul_f32_e32 v209, v8, v237
	s_waitcnt vmcnt(7)
	v_mul_f32_e32 v206, v209, v145
	v_mul_f32_e32 v207, v208, v145
	v_fma_f32 v206, v208, v144, -v206
	v_fma_f32 v207, v209, v144, v207
	v_cvt_pk_bf16_f32 v206, v206, v207
	ds_write_b16 v201, v206 offset:2304
	ds_write_b16_d16_hi v201, v206 offset:2368
	v_mul_f32_e32 v208, v25, v238
	v_mul_f32_e32 v209, v9, v238
	s_waitcnt vmcnt(6)
	v_mul_f32_e32 v206, v209, v147
	v_mul_f32_e32 v207, v208, v147
	v_fma_f32 v206, v208, v146, -v206
	v_fma_f32 v207, v209, v146, v207
	v_cvt_pk_bf16_f32 v206, v206, v207
	ds_write_b16 v201, v206 offset:2448
	ds_write_b16_d16_hi v201, v206 offset:2512
	v_mul_f32_e32 v208, v26, v239
	v_mul_f32_e32 v209, v10, v239
	s_waitcnt vmcnt(5)
	v_mul_f32_e32 v206, v209, v149
	v_mul_f32_e32 v207, v208, v149
	v_fma_f32 v206, v208, v148, -v206
	v_fma_f32 v207, v209, v148, v207
	v_cvt_pk_bf16_f32 v206, v206, v207
	ds_write_b16 v201, v206 offset:2592
	ds_write_b16_d16_hi v201, v206 offset:2656
	v_mul_f32_e32 v208, v27, v240
	v_mul_f32_e32 v209, v11, v240
	s_waitcnt vmcnt(4)
	v_mul_f32_e32 v206, v209, v151
	v_mul_f32_e32 v207, v208, v151
	v_fma_f32 v206, v208, v150, -v206
	v_fma_f32 v207, v209, v150, v207
	v_cvt_pk_bf16_f32 v206, v206, v207
	ds_write_b16 v201, v206 offset:2736
	ds_write_b16_d16_hi v201, v206 offset:2800
	v_mul_f32_e32 v208, v28, v241
	v_mul_f32_e32 v209, v12, v241
	s_waitcnt vmcnt(3)
	v_mul_f32_e32 v206, v209, v153
	v_mul_f32_e32 v207, v208, v153
	v_fma_f32 v206, v208, v152, -v206
	v_fma_f32 v207, v209, v152, v207
	v_cvt_pk_bf16_f32 v206, v206, v207
	ds_write_b16 v201, v206 offset:3456
	ds_write_b16_d16_hi v201, v206 offset:3520
	v_mul_f32_e32 v208, v29, v242
	v_mul_f32_e32 v209, v13, v242
	s_waitcnt vmcnt(2)
	v_mul_f32_e32 v206, v209, v155
	v_mul_f32_e32 v207, v208, v155
	v_fma_f32 v206, v208, v154, -v206
	v_fma_f32 v207, v209, v154, v207
	v_cvt_pk_bf16_f32 v206, v206, v207
	ds_write_b16 v201, v206 offset:3600
	ds_write_b16_d16_hi v201, v206 offset:3664
	v_mul_f32_e32 v208, v30, v243
	v_mul_f32_e32 v209, v14, v243
	s_waitcnt vmcnt(1)
	v_mul_f32_e32 v206, v209, v157
	v_mul_f32_e32 v207, v208, v157
	v_fma_f32 v206, v208, v156, -v206
	v_fma_f32 v207, v209, v156, v207
	v_cvt_pk_bf16_f32 v206, v206, v207
	ds_write_b16 v201, v206 offset:3744
	ds_write_b16_d16_hi v201, v206 offset:3808
	v_mul_f32_e32 v208, v31, v244
	v_mul_f32_e32 v209, v15, v244
	s_waitcnt vmcnt(0)
	v_mul_f32_e32 v206, v209, v159
	v_mul_f32_e32 v207, v208, v159
	v_fma_f32 v206, v208, v158, -v206
	v_fma_f32 v207, v209, v158, v207
	v_cvt_pk_bf16_f32 v206, v206, v207
	ds_write_b16 v201, v206 offset:3888
	ds_write_b16_d16_hi v201, v206 offset:3952
.Lmq3q_e11_st:
	v_mad_u32_u24 v211, v204, s99, v205
	s_lshl_b32 s99, s99, 3
	ds_read_b128 v[160:163], v202
	ds_read_b128 v[164:167], v202 offset:1152
	ds_read_b128 v[168:171], v202 offset:2304
	ds_read_b128 v[172:175], v202 offset:3456
	v_add_u32_e32 v206, s89, v211
	s_add_u32 s89, s89, s99
	v_add_u32_e32 v207, s89, v211
	s_add_u32 s89, s89, s99
	v_add_u32_e32 v208, s89, v211
	s_add_u32 s89, s89, s99
	v_add_u32_e32 v209, s89, v211
	s_waitcnt lgkmcnt(3)
	global_store_dwordx4 v206, v[160:163], s[2:3]
	s_waitcnt lgkmcnt(2)
	global_store_dwordx4 v207, v[164:167], s[2:3]
	s_waitcnt lgkmcnt(1)
	global_store_dwordx4 v208, v[168:171], s[2:3]
	s_waitcnt lgkmcnt(0)
	global_store_dwordx4 v209, v[172:175], s[2:3]
	s_add_u32 s30, s30, s42
	s_cmp_lt_u32 s30, 768
	s_cbranch_scc1 .Lmq3q_tile
.Lmq3q_done:
	s_load_dwordx2 s[4:5], s[0:1], 0x170
	s_load_dwordx2 s[6:7], s[0:1], 0xe0
	s_load_dwordx2 s[8:9], s[0:1], 0x218
	s_load_dwordx2 s[10:11], s[0:1], 0x148
	s_load_dwordx2 s[12:13], s[0:1], 0x180
	s_load_dwordx2 s[14:15], s[0:1], 0x188
	s_lshl_b32 s96, s29, 3
	v_add_u32_e32 v206, s96, v204
	v_xor_b32_e32 v207, v245, v205
	v_lshl_add_u32 v192, v206, 8, v207
	v_mov_b32_e32 v193, 0
	v_add_u32_e32 v208, 64, v206
	v_lshl_add_u32 v194, v208, 8, v207
	v_mov_b32_e32 v195, 0
	v_add_u32_e32 v208, 128, v206
	v_lshl_add_u32 v196, v208, 8, v207
	v_mov_b32_e32 v197, 0
	v_add_u32_e32 v208, 192, v206
	v_lshl_add_u32 v198, v208, 8, v207
	v_mov_b32_e32 v199, 0
	s_mov_b32 s30, s28
	s_cmp_ge_u32 s30, 1024
	s_cbranch_scc1 .Lmq3k_done
	s_waitcnt lgkmcnt(0)
	s_lshr_b32 s35, s30, 3
	s_mul_i32 s36, s35, 8
	s_sub_u32 s36, s30, s36
	s_lshl_b32 s98, s35, 16
	s_add_u32 s16, s4, s98
	s_addc_u32 s17, s5, 0
	s_lshl_b32 s98, s36, 16
	s_add_u32 s18, s6, s98
	s_addc_u32 s19, s7, 0
	s_add_u32 m0, s88, 0
	v_lshl_add_u64 v[152:153], v[192:193], 0, s[16:17]
	global_load_lds_dwordx4 v[152:153], off
	s_add_u32 m0, s88, 32768
	v_lshl_add_u64 v[154:155], v[192:193], 0, s[18:19]
	global_load_lds_dwordx4 v[154:155], off
	s_add_u32 m0, s88, 8192
	v_lshl_add_u64 v[156:157], v[194:195], 0, s[16:17]
	global_load_lds_dwordx4 v[156:157], off
	s_add_u32 m0, s88, 40960
	v_lshl_add_u64 v[152:153], v[194:195], 0, s[18:19]
	global_load_lds_dwordx4 v[152:153], off
	s_add_u32 m0, s88, 16384
	v_lshl_add_u64 v[154:155], v[196:197], 0, s[16:17]
	global_load_lds_dwordx4 v[154:155], off
	s_add_u32 m0, s88, 49152
	v_lshl_add_u64 v[156:157], v[196:197], 0, s[18:19]
	global_load_lds_dwordx4 v[156:157], off
	s_add_u32 m0, s88, 24576
	v_lshl_add_u64 v[152:153], v[198:199], 0, s[16:17]
	global_load_lds_dwordx4 v[152:153], off
	s_add_u32 m0, s88, 57344
	v_lshl_add_u64 v[154:155], v[198:199], 0, s[18:19]
	global_load_lds_dwordx4 v[154:155], off
.Lmq3k_tile:
	s_lshr_b32 s35, s30, 3
	s_mul_i32 s36, s35, 8
	s_sub_u32 s36, s30, s36
	s_lshl_b32 s92, s35, 8
	s_add_u32 s92, s92, s31
	s_lshl_b32 s93, s36, 8
	s_add_u32 s93, s93, s34
	s_lshl_b32 s96, s92, 2
	v_lshl_add_u32 v212, v203, 2, s96
	s_waitcnt vmcnt(0)
	s_barrier
	s_add_u32 s20, s16, 128
	s_addc_u32 s21, s17, 0
	s_add_u32 s24, s18, 128
	s_addc_u32 s25, s19, 0
	s_add_u32 m0, s88, 65536
	v_lshl_add_u64 v[152:153], v[192:193], 0, s[20:21]
	global_load_lds_dwordx4 v[152:153], off
	s_add_u32 m0, s88, 98304
	v_lshl_add_u64 v[154:155], v[192:193], 0, s[24:25]
	global_load_lds_dwordx4 v[154:155], off
	s_add_u32 m0, s88, 73728
	v_lshl_add_u64 v[156:157], v[194:195], 0, s[20:21]
	global_load_lds_dwordx4 v[156:157], off
	s_add_u32 m0, s88, 106496
	v_lshl_add_u64 v[152:153], v[194:195], 0, s[24:25]
	global_load_lds_dwordx4 v[152:153], off
	s_add_u32 m0, s88, 81920
	v_lshl_add_u64 v[154:155], v[196:197], 0, s[20:21]
	global_load_lds_dwordx4 v[154:155], off
	s_add_u32 m0, s88, 114688
	v_lshl_add_u64 v[156:157], v[196:197], 0, s[24:25]
	global_load_lds_dwordx4 v[156:157], off
	s_add_u32 m0, s88, 90112
	v_lshl_add_u64 v[152:153], v[198:199], 0, s[20:21]
	global_load_lds_dwordx4 v[152:153], off
	s_add_u32 m0, s88, 122880
	v_lshl_add_u64 v[154:155], v[198:199], 0, s[24:25]
	global_load_lds_dwordx4 v[154:155], off
	global_load_dword v213, v212, s[8:9] offset:0
	global_load_dword v214, v212, s[8:9] offset:4
	global_load_dword v215, v212, s[8:9] offset:8
	global_load_dword v216, v212, s[8:9] offset:12
	global_load_dword v217, v212, s[8:9] offset:32
	global_load_dword v218, v212, s[8:9] offset:36
	global_load_dword v219, v212, s[8:9] offset:40
	global_load_dword v220, v212, s[8:9] offset:44
	global_load_dword v221, v212, s[8:9] offset:64
	global_load_dword v222, v212, s[8:9] offset:68
	global_load_dword v223, v212, s[8:9] offset:72
	global_load_dword v224, v212, s[8:9] offset:76
	global_load_dword v225, v212, s[8:9] offset:96
	global_load_dword v226, v212, s[8:9] offset:100
	global_load_dword v227, v212, s[8:9] offset:104
	global_load_dword v228, v212, s[8:9] offset:108
	global_load_dword v229, v212, s[8:9] offset:128
	global_load_dword v230, v212, s[8:9] offset:132
	global_load_dword v231, v212, s[8:9] offset:136
	global_load_dword v232, v212, s[8:9] offset:140
	global_load_dword v233, v212, s[8:9] offset:160
	global_load_dword v234, v212, s[8:9] offset:164
	global_load_dword v235, v212, s[8:9] offset:168
	global_load_dword v236, v212, s[8:9] offset:172
	global_load_dword v237, v212, s[8:9] offset:192
	global_load_dword v238, v212, s[8:9] offset:196
	global_load_dword v239, v212, s[8:9] offset:200
	global_load_dword v240, v212, s[8:9] offset:204
	global_load_dword v241, v212, s[8:9] offset:224
	global_load_dword v242, v212, s[8:9] offset:228
	global_load_dword v243, v212, s[8:9] offset:232
	global_load_dword v244, v212, s[8:9] offset:236
	ds_read_b128 v[160:163], v184
	ds_read_b128 v[168:171], v188
	ds_read_b128 v[164:167], v184 offset:4096
	ds_read_b128 v[172:175], v188 offset:4096
	ds_read_b128 v[176:179], v188 offset:8192
	ds_read_b128 v[180:183], v188 offset:12288
	ds_read_b128 v[128:131], v185
	ds_read_b128 v[136:139], v189
	ds_read_b128 v[132:135], v185 offset:4096
	ds_read_b128 v[140:143], v189 offset:4096
	ds_read_b128 v[144:147], v189 offset:8192
	ds_read_b128 v[148:151], v189 offset:12288
	s_waitcnt lgkmcnt(6)
	v_mfma_f32_32x32x16_bf16 v[112:127], v[160:163], v[168:171], 0
	v_mfma_f32_32x32x16_bf16 v[48:63], v[164:167], v[168:171], 0
	v_mfma_f32_32x32x16_bf16 v[96:111], v[160:163], v[172:175], 0
	v_mfma_f32_32x32x16_bf16 v[32:47], v[164:167], v[172:175], 0
	v_mfma_f32_32x32x16_bf16 v[80:95], v[160:163], v[176:179], 0
	v_mfma_f32_32x32x16_bf16 v[16:31], v[164:167], v[176:179], 0
	v_mfma_f32_32x32x16_bf16 v[64:79], v[160:163], v[180:183], 0
	v_mfma_f32_32x32x16_bf16 v[0:15], v[164:167], v[180:183], 0
	ds_read_b128 v[160:163], v186
	ds_read_b128 v[168:171], v190
	ds_read_b128 v[164:167], v186 offset:4096
	ds_read_b128 v[172:175], v190 offset:4096
	ds_read_b128 v[176:179], v190 offset:8192
	ds_read_b128 v[180:183], v190 offset:12288
	s_waitcnt lgkmcnt(6)
	v_mfma_f32_32x32x16_bf16 v[112:127], v[128:131], v[136:139], v[112:127]
	v_mfma_f32_32x32x16_bf16 v[48:63], v[132:135], v[136:139], v[48:63]
	v_mfma_f32_32x32x16_bf16 v[96:111], v[128:131], v[140:143], v[96:111]
	v_mfma_f32_32x32x16_bf16 v[32:47], v[132:135], v[140:143], v[32:47]
	v_mfma_f32_32x32x16_bf16 v[80:95], v[128:131], v[144:147], v[80:95]
	v_mfma_f32_32x32x16_bf16 v[16:31], v[132:135], v[144:147], v[16:31]
	v_mfma_f32_32x32x16_bf16 v[64:79], v[128:131], v[148:151], v[64:79]
	v_mfma_f32_32x32x16_bf16 v[0:15], v[132:135], v[148:151], v[0:15]
	ds_read_b128 v[128:131], v187
	ds_read_b128 v[136:139], v191
	ds_read_b128 v[132:135], v187 offset:4096
	ds_read_b128 v[140:143], v191 offset:4096
	ds_read_b128 v[144:147], v191 offset:8192
	ds_read_b128 v[148:151], v191 offset:12288
	s_waitcnt lgkmcnt(6)
	v_mfma_f32_32x32x16_bf16 v[112:127], v[160:163], v[168:171], v[112:127]
	v_mfma_f32_32x32x16_bf16 v[48:63], v[164:167], v[168:171], v[48:63]
	v_mfma_f32_32x32x16_bf16 v[96:111], v[160:163], v[172:175], v[96:111]
	v_mfma_f32_32x32x16_bf16 v[32:47], v[164:167], v[172:175], v[32:47]
	v_mfma_f32_32x32x16_bf16 v[80:95], v[160:163], v[176:179], v[80:95]
	v_mfma_f32_32x32x16_bf16 v[16:31], v[164:167], v[176:179], v[16:31]
	v_mfma_f32_32x32x16_bf16 v[64:79], v[160:163], v[180:183], v[64:79]
	v_mfma_f32_32x32x16_bf16 v[0:15], v[164:167], v[180:183], v[0:15]
	s_waitcnt vmcnt(0) lgkmcnt(0)
	s_barrier
	v_xor_b32_e32 v184, 0x10000, v184
	v_xor_b32_e32 v188, 0x10000, v188
	ds_read_b128 v[160:163], v184
	ds_read_b128 v[168:171], v188
	ds_read_b128 v[164:167], v184 offset:4096
	ds_read_b128 v[172:175], v188 offset:4096
	ds_read_b128 v[176:179], v188 offset:8192
	ds_read_b128 v[180:183], v188 offset:12288
	s_add_u32 s37, s30, s42
	s_cmp_ge_u32 s37, 1024
	s_cbranch_scc1 .Lmq3k_nonext0
	s_lshr_b32 s38, s37, 3
	s_mul_i32 s39, s38, 8
	s_sub_u32 s39, s37, s39
	s_lshl_b32 s98, s38, 16
	s_add_u32 s16, s4, s98
	s_addc_u32 s17, s5, 0
	s_lshl_b32 s98, s39, 16
	s_add_u32 s18, s6, s98
	s_addc_u32 s19, s7, 0
	v_mfma_f32_32x32x16_bf16 v[112:127], v[128:131], v[136:139], v[112:127]
	v_xor_b32_e32 v185, 0x10000, v185
	v_xor_b32_e32 v189, 0x10000, v189
	s_add_u32 m0, s88, 0
	v_lshl_add_u64 v[152:153], v[192:193], 0, s[16:17]
	global_load_lds_dwordx4 v[152:153], off
	v_mfma_f32_32x32x16_bf16 v[48:63], v[132:135], v[136:139], v[48:63]
	v_xor_b32_e32 v186, 0x10000, v186
	v_xor_b32_e32 v190, 0x10000, v190
	s_add_u32 m0, s88, 32768
	v_lshl_add_u64 v[154:155], v[192:193], 0, s[18:19]
	global_load_lds_dwordx4 v[154:155], off
	v_mfma_f32_32x32x16_bf16 v[96:111], v[128:131], v[140:143], v[96:111]
	v_xor_b32_e32 v187, 0x10000, v187
	v_xor_b32_e32 v191, 0x10000, v191
	s_add_u32 m0, s88, 8192
	v_lshl_add_u64 v[156:157], v[194:195], 0, s[16:17]
	global_load_lds_dwordx4 v[156:157], off
	v_mfma_f32_32x32x16_bf16 v[32:47], v[132:135], v[140:143], v[32:47]
	s_add_u32 m0, s88, 40960
	v_lshl_add_u64 v[152:153], v[194:195], 0, s[18:19]
	global_load_lds_dwordx4 v[152:153], off
	v_mfma_f32_32x32x16_bf16 v[80:95], v[128:131], v[144:147], v[80:95]
	s_add_u32 m0, s88, 16384
	v_lshl_add_u64 v[154:155], v[196:197], 0, s[16:17]
	global_load_lds_dwordx4 v[154:155], off
	v_mfma_f32_32x32x16_bf16 v[16:31], v[132:135], v[144:147], v[16:31]
	s_add_u32 m0, s88, 49152
	v_lshl_add_u64 v[156:157], v[196:197], 0, s[18:19]
	global_load_lds_dwordx4 v[156:157], off
	v_mfma_f32_32x32x16_bf16 v[64:79], v[128:131], v[148:151], v[64:79]
	s_add_u32 m0, s88, 24576
	v_lshl_add_u64 v[152:153], v[198:199], 0, s[16:17]
	global_load_lds_dwordx4 v[152:153], off
	v_mfma_f32_32x32x16_bf16 v[0:15], v[132:135], v[148:151], v[0:15]
	s_add_u32 m0, s88, 57344
	v_lshl_add_u64 v[154:155], v[198:199], 0, s[18:19]
	global_load_lds_dwordx4 v[154:155], off
	s_branch .Lmq3k_join0

.Lmq3k_join0:
	ds_read_b128 v[128:131], v185
	ds_read_b128 v[136:139], v189
	ds_read_b128 v[132:135], v185 offset:4096
	ds_read_b128 v[140:143], v189 offset:4096
	ds_read_b128 v[144:147], v189 offset:8192
	ds_read_b128 v[148:151], v189 offset:12288
	s_waitcnt lgkmcnt(6)
	v_mfma_f32_32x32x16_bf16 v[112:127], v[160:163], v[168:171], v[112:127]
	v_mfma_f32_32x32x16_bf16 v[48:63], v[164:167], v[168:171], v[48:63]
	v_mfma_f32_32x32x16_bf16 v[96:111], v[160:163], v[172:175], v[96:111]
	v_mfma_f32_32x32x16_bf16 v[32:47], v[164:167], v[172:175], v[32:47]
	v_mfma_f32_32x32x16_bf16 v[80:95], v[160:163], v[176:179], v[80:95]
	v_mfma_f32_32x32x16_bf16 v[16:31], v[164:167], v[176:179], v[16:31]
	v_mfma_f32_32x32x16_bf16 v[64:79], v[160:163], v[180:183], v[64:79]
	v_mfma_f32_32x32x16_bf16 v[0:15], v[164:167], v[180:183], v[0:15]
	ds_read_b128 v[160:163], v186
	ds_read_b128 v[168:171], v190
	ds_read_b128 v[164:167], v186 offset:4096
	ds_read_b128 v[172:175], v190 offset:4096
	ds_read_b128 v[176:179], v190 offset:8192
	ds_read_b128 v[180:183], v190 offset:12288
	s_waitcnt lgkmcnt(6)
	v_mfma_f32_32x32x16_bf16 v[112:127], v[128:131], v[136:139], v[112:127]
	v_mfma_f32_32x32x16_bf16 v[48:63], v[132:135], v[136:139], v[48:63]
	v_mfma_f32_32x32x16_bf16 v[96:111], v[128:131], v[140:143], v[96:111]
	v_mfma_f32_32x32x16_bf16 v[32:47], v[132:135], v[140:143], v[32:47]
	v_mfma_f32_32x32x16_bf16 v[80:95], v[128:131], v[144:147], v[80:95]
	v_mfma_f32_32x32x16_bf16 v[16:31], v[132:135], v[144:147], v[16:31]
	v_mfma_f32_32x32x16_bf16 v[64:79], v[128:131], v[148:151], v[64:79]
	v_mfma_f32_32x32x16_bf16 v[0:15], v[132:135], v[148:151], v[0:15]
	ds_read_b128 v[128:131], v187
	ds_read_b128 v[136:139], v191
	ds_read_b128 v[132:135], v187 offset:4096
	ds_read_b128 v[140:143], v191 offset:4096
	ds_read_b128 v[144:147], v191 offset:8192
	ds_read_b128 v[148:151], v191 offset:12288
	s_waitcnt lgkmcnt(6)
	v_mfma_f32_32x32x16_bf16 v[112:127], v[160:163], v[168:171], v[112:127]
	v_mfma_f32_32x32x16_bf16 v[48:63], v[164:167], v[168:171], v[48:63]
	v_mfma_f32_32x32x16_bf16 v[96:111], v[160:163], v[172:175], v[96:111]
	v_mfma_f32_32x32x16_bf16 v[32:47], v[164:167], v[172:175], v[32:47]
	v_mfma_f32_32x32x16_bf16 v[80:95], v[160:163], v[176:179], v[80:95]
	v_mfma_f32_32x32x16_bf16 v[16:31], v[164:167], v[176:179], v[16:31]
	v_mfma_f32_32x32x16_bf16 v[64:79], v[160:163], v[180:183], v[64:79]
	v_mfma_f32_32x32x16_bf16 v[0:15], v[164:167], v[180:183], v[0:15]
	s_waitcnt vmcnt(0) lgkmcnt(0)
	s_barrier
	v_xor_b32_e32 v184, 0x10000, v184
	v_xor_b32_e32 v188, 0x10000, v188
	v_mfma_f32_32x32x16_bf16 v[112:127], v[128:131], v[136:139], v[112:127]
	v_xor_b32_e32 v185, 0x10000, v185
	v_xor_b32_e32 v189, 0x10000, v189
	v_mul_f32_e32 v213, 0x3c000000, v213
	v_mul_f32_e32 v214, 0x3c000000, v214
	v_mul_f32_e32 v215, 0x3c000000, v215
	v_mul_f32_e32 v216, 0x3c000000, v216
	v_add_f32_e32 v213, 0x358637bd, v213
	v_add_f32_e32 v214, 0x358637bd, v214
	v_add_f32_e32 v215, 0x358637bd, v215
	v_add_f32_e32 v216, 0x358637bd, v216
	v_rsq_f32_e32 v213, v213
	v_rsq_f32_e32 v214, v214
	v_rsq_f32_e32 v215, v215
	v_rsq_f32_e32 v216, v216
	v_mfma_f32_32x32x16_bf16 v[48:63], v[132:135], v[136:139], v[48:63]
	v_xor_b32_e32 v186, 0x10000, v186
	v_xor_b32_e32 v190, 0x10000, v190
	v_mul_f32_e32 v217, 0x3c000000, v217
	v_mul_f32_e32 v218, 0x3c000000, v218
	v_mul_f32_e32 v219, 0x3c000000, v219
	v_mul_f32_e32 v220, 0x3c000000, v220
	v_add_f32_e32 v217, 0x358637bd, v217
	v_add_f32_e32 v218, 0x358637bd, v218
	v_add_f32_e32 v219, 0x358637bd, v219
	v_add_f32_e32 v220, 0x358637bd, v220
	v_rsq_f32_e32 v217, v217
	v_rsq_f32_e32 v218, v218
	v_rsq_f32_e32 v219, v219
	v_rsq_f32_e32 v220, v220
	v_mfma_f32_32x32x16_bf16 v[96:111], v[128:131], v[140:143], v[96:111]
	v_xor_b32_e32 v187, 0x10000, v187
	v_xor_b32_e32 v191, 0x10000, v191
	v_mul_f32_e32 v221, 0x3c000000, v221
	v_mul_f32_e32 v222, 0x3c000000, v222
	v_mul_f32_e32 v223, 0x3c000000, v223
	v_mul_f32_e32 v224, 0x3c000000, v224
	v_add_f32_e32 v221, 0x358637bd, v221
	v_add_f32_e32 v222, 0x358637bd, v222
	v_add_f32_e32 v223, 0x358637bd, v223
	v_add_f32_e32 v224, 0x358637bd, v224
	v_rsq_f32_e32 v221, v221
	v_rsq_f32_e32 v222, v222
	v_rsq_f32_e32 v223, v223
	v_rsq_f32_e32 v224, v224
	v_mfma_f32_32x32x16_bf16 v[32:47], v[132:135], v[140:143], v[32:47]
	v_mul_f32_e32 v225, 0x3c000000, v225
	v_mul_f32_e32 v226, 0x3c000000, v226
	v_mul_f32_e32 v227, 0x3c000000, v227
	v_mul_f32_e32 v228, 0x3c000000, v228
	v_add_f32_e32 v225, 0x358637bd, v225
	v_add_f32_e32 v226, 0x358637bd, v226
	v_add_f32_e32 v227, 0x358637bd, v227
	v_add_f32_e32 v228, 0x358637bd, v228
	v_rsq_f32_e32 v225, v225
	v_rsq_f32_e32 v226, v226
	v_rsq_f32_e32 v227, v227
	v_rsq_f32_e32 v228, v228
	v_mfma_f32_32x32x16_bf16 v[80:95], v[128:131], v[144:147], v[80:95]
	v_mul_f32_e32 v229, 0x3c000000, v229
	v_mul_f32_e32 v230, 0x3c000000, v230
	v_mul_f32_e32 v231, 0x3c000000, v231
	v_mul_f32_e32 v232, 0x3c000000, v232
	v_add_f32_e32 v229, 0x358637bd, v229
	v_add_f32_e32 v230, 0x358637bd, v230
	v_add_f32_e32 v231, 0x358637bd, v231
	v_add_f32_e32 v232, 0x358637bd, v232
	v_rsq_f32_e32 v229, v229
	v_rsq_f32_e32 v230, v230
	v_rsq_f32_e32 v231, v231
	v_rsq_f32_e32 v232, v232
	v_mfma_f32_32x32x16_bf16 v[16:31], v[132:135], v[144:147], v[16:31]
	v_mul_f32_e32 v233, 0x3c000000, v233
	v_mul_f32_e32 v234, 0x3c000000, v234
	v_mul_f32_e32 v235, 0x3c000000, v235
	v_mul_f32_e32 v236, 0x3c000000, v236
	v_add_f32_e32 v233, 0x358637bd, v233
	v_add_f32_e32 v234, 0x358637bd, v234
	v_add_f32_e32 v235, 0x358637bd, v235
	v_add_f32_e32 v236, 0x358637bd, v236
	v_rsq_f32_e32 v233, v233
	v_rsq_f32_e32 v234, v234
	v_rsq_f32_e32 v235, v235
	v_rsq_f32_e32 v236, v236
	v_mfma_f32_32x32x16_bf16 v[64:79], v[128:131], v[148:151], v[64:79]
	v_mul_f32_e32 v237, 0x3c000000, v237
	v_mul_f32_e32 v238, 0x3c000000, v238
	v_mul_f32_e32 v239, 0x3c000000, v239
	v_mul_f32_e32 v240, 0x3c000000, v240
	v_add_f32_e32 v237, 0x358637bd, v237
	v_add_f32_e32 v238, 0x358637bd, v238
	v_add_f32_e32 v239, 0x358637bd, v239
	v_add_f32_e32 v240, 0x358637bd, v240
	v_rsq_f32_e32 v237, v237
	v_rsq_f32_e32 v238, v238
	v_rsq_f32_e32 v239, v239
	v_rsq_f32_e32 v240, v240
	v_mfma_f32_32x32x16_bf16 v[0:15], v[132:135], v[148:151], v[0:15]
	v_mul_f32_e32 v241, 0x3c000000, v241
	v_mul_f32_e32 v242, 0x3c000000, v242
	v_mul_f32_e32 v243, 0x3c000000, v243
	v_mul_f32_e32 v244, 0x3c000000, v244
	v_add_f32_e32 v241, 0x358637bd, v241
	v_add_f32_e32 v242, 0x358637bd, v242
	v_add_f32_e32 v243, 0x358637bd, v243
	v_add_f32_e32 v244, 0x358637bd, v244
	v_rsq_f32_e32 v241, v241
	v_rsq_f32_e32 v242, v242
	v_rsq_f32_e32 v243, v243
	v_rsq_f32_e32 v244, v244
	s_nop 7
	s_add_u32 s94, s92, 0
	s_add_u32 s95, s93, 0
	s_lshr_b32 s90, s95, 6
	s_lshr_b32 s96, s94, 12
	s_and_b32 s97, s94, 0xfff
	s_lshr_b32 s91, s90, 2
	s_and_b32 s98, s90, 3
	s_cmp_lt_u32 s98, 2
	s_cbranch_scc0 .Lmq3k_e00_v
	s_mul_i32 s89, s96, 0xc00000
	s_mul_i32 s91, s91, 0x180000
	s_add_u32 s89, s89, s91
	s_lshl_b32 s91, s98, 7
	s_add_u32 s89, s89, s91
	s_mul_i32 s91, s97, 0x180
	s_add_u32 s89, s89, s91
	s_movk_i32 s99, 0x180
	s_mov_b64 s[2:3], s[12:13]
	s_branch .Lmq3k_e00_plain
.Lmq3k_e00_v:
	s_mul_i32 s89, s96, 0x800000
	s_mul_i32 s91, s91, 0x100000
	s_add_u32 s89, s89, s91
	s_sub_u32 s91, s98, 2
	s_lshl_b32 s91, s91, 7
	s_add_u32 s89, s89, s91
	s_lshl_b32 s91, s97, 8
	s_add_u32 s89, s89, s91
	s_movk_i32 s99, 0x100
	s_mov_b64 s[2:3], s[14:15]
.Lmq3k_e00_plain:
	v_mul_f32_e32 v206, v112, v213
	v_mul_f32_e32 v207, v96, v213
	v_cvt_pk_bf16_f32 v206, v206, v207
	ds_write_b16 v201, v206
	ds_write_b16_d16_hi v201, v206 offset:64
	v_mul_f32_e32 v208, v113, v214
	v_mul_f32_e32 v209, v97, v214
	v_cvt_pk_bf16_f32 v208, v208, v209
	ds_write_b16 v201, v208 offset:144
	ds_write_b16_d16_hi v201, v208 offset:208
	v_mul_f32_e32 v206, v114, v215
	v_mul_f32_e32 v207, v98, v215
	v_cvt_pk_bf16_f32 v206, v206, v207
	ds_write_b16 v201, v206 offset:288
	ds_write_b16_d16_hi v201, v206 offset:352
	v_mul_f32_e32 v208, v115, v216
	v_mul_f32_e32 v209, v99, v216
	v_cvt_pk_bf16_f32 v208, v208, v209
	ds_write_b16 v201, v208 offset:432
	ds_write_b16_d16_hi v201, v208 offset:496
	v_mul_f32_e32 v206, v116, v217
	v_mul_f32_e32 v207, v100, v217
	v_cvt_pk_bf16_f32 v206, v206, v207
	ds_write_b16 v201, v206 offset:1152
	ds_write_b16_d16_hi v201, v206 offset:1216
	v_mul_f32_e32 v208, v117, v218
	v_mul_f32_e32 v209, v101, v218
	v_cvt_pk_bf16_f32 v208, v208, v209
	ds_write_b16 v201, v208 offset:1296
	ds_write_b16_d16_hi v201, v208 offset:1360
	v_mul_f32_e32 v206, v118, v219
	v_mul_f32_e32 v207, v102, v219
	v_cvt_pk_bf16_f32 v206, v206, v207
	ds_write_b16 v201, v206 offset:1440
	ds_write_b16_d16_hi v201, v206 offset:1504
	v_mul_f32_e32 v208, v119, v220
	v_mul_f32_e32 v209, v103, v220
	v_cvt_pk_bf16_f32 v208, v208, v209
	ds_write_b16 v201, v208 offset:1584
	ds_write_b16_d16_hi v201, v208 offset:1648
	v_mul_f32_e32 v206, v120, v221
	v_mul_f32_e32 v207, v104, v221
	v_cvt_pk_bf16_f32 v206, v206, v207
	ds_write_b16 v201, v206 offset:2304
	ds_write_b16_d16_hi v201, v206 offset:2368
	v_mul_f32_e32 v208, v121, v222
	v_mul_f32_e32 v209, v105, v222
	v_cvt_pk_bf16_f32 v208, v208, v209
	ds_write_b16 v201, v208 offset:2448
	ds_write_b16_d16_hi v201, v208 offset:2512
	v_mul_f32_e32 v206, v122, v223
	v_mul_f32_e32 v207, v106, v223
	v_cvt_pk_bf16_f32 v206, v206, v207
	ds_write_b16 v201, v206 offset:2592
	ds_write_b16_d16_hi v201, v206 offset:2656
	v_mul_f32_e32 v208, v123, v224
	v_mul_f32_e32 v209, v107, v224
	v_cvt_pk_bf16_f32 v208, v208, v209
	ds_write_b16 v201, v208 offset:2736
	ds_write_b16_d16_hi v201, v208 offset:2800
	v_mul_f32_e32 v206, v124, v225
	v_mul_f32_e32 v207, v108, v225
	v_cvt_pk_bf16_f32 v206, v206, v207
	ds_write_b16 v201, v206 offset:3456
	ds_write_b16_d16_hi v201, v206 offset:3520
	v_mul_f32_e32 v208, v125, v226
	v_mul_f32_e32 v209, v109, v226
	v_cvt_pk_bf16_f32 v208, v208, v209
	ds_write_b16 v201, v208 offset:3600
	ds_write_b16_d16_hi v201, v208 offset:3664
	v_mul_f32_e32 v206, v126, v227
	v_mul_f32_e32 v207, v110, v227
	v_cvt_pk_bf16_f32 v206, v206, v207
	ds_write_b16 v201, v206 offset:3744
	ds_write_b16_d16_hi v201, v206 offset:3808
	v_mul_f32_e32 v208, v127, v228
	v_mul_f32_e32 v209, v111, v228
	v_cvt_pk_bf16_f32 v208, v208, v209
	ds_write_b16 v201, v208 offset:3888
	ds_write_b16_d16_hi v201, v208 offset:3952
.Lmq3k_e00_st:
	v_mad_u32_u24 v211, v204, s99, v205
	s_lshl_b32 s99, s99, 3
	ds_read_b128 v[160:163], v202
	ds_read_b128 v[164:167], v202 offset:1152
	ds_read_b128 v[168:171], v202 offset:2304
	ds_read_b128 v[172:175], v202 offset:3456
	v_add_u32_e32 v206, s89, v211
	s_add_u32 s89, s89, s99
	v_add_u32_e32 v207, s89, v211
	s_add_u32 s89, s89, s99
	v_add_u32_e32 v208, s89, v211
	s_add_u32 s89, s89, s99
	v_add_u32_e32 v209, s89, v211
	s_waitcnt lgkmcnt(3)
	global_store_dwordx4 v206, v[160:163], s[2:3]
	s_waitcnt lgkmcnt(2)
	global_store_dwordx4 v207, v[164:167], s[2:3]
	s_waitcnt lgkmcnt(1)
	global_store_dwordx4 v208, v[168:171], s[2:3]
	s_waitcnt lgkmcnt(0)
	global_store_dwordx4 v209, v[172:175], s[2:3]
	s_add_u32 s94, s92, 0
	s_add_u32 s95, s93, 64
	s_lshr_b32 s90, s95, 6
	s_lshr_b32 s96, s94, 12
	s_and_b32 s97, s94, 0xfff
	s_lshr_b32 s91, s90, 2
	s_and_b32 s98, s90, 3
	s_cmp_lt_u32 s98, 2
	s_cbranch_scc0 .Lmq3k_e01_v
	s_mul_i32 s89, s96, 0xc00000
	s_mul_i32 s91, s91, 0x180000
	s_add_u32 s89, s89, s91
	s_lshl_b32 s91, s98, 7
	s_add_u32 s89, s89, s91
	s_mul_i32 s91, s97, 0x180
	s_add_u32 s89, s89, s91
	s_movk_i32 s99, 0x180
	s_mov_b64 s[2:3], s[12:13]
	s_branch .Lmq3k_e01_plain

.Lmq3k_e01_plain:
	v_mul_f32_e32 v206, v80, v213
	v_mul_f32_e32 v207, v64, v213
	v_cvt_pk_bf16_f32 v206, v206, v207
	ds_write_b16 v201, v206
	ds_write_b16_d16_hi v201, v206 offset:64
	v_mul_f32_e32 v208, v81, v214
	v_mul_f32_e32 v209, v65, v214
	v_cvt_pk_bf16_f32 v208, v208, v209
	ds_write_b16 v201, v208 offset:144
	ds_write_b16_d16_hi v201, v208 offset:208
	v_mul_f32_e32 v206, v82, v215
	v_mul_f32_e32 v207, v66, v215
	v_cvt_pk_bf16_f32 v206, v206, v207
	ds_write_b16 v201, v206 offset:288
	ds_write_b16_d16_hi v201, v206 offset:352
	v_mul_f32_e32 v208, v83, v216
	v_mul_f32_e32 v209, v67, v216
	v_cvt_pk_bf16_f32 v208, v208, v209
	ds_write_b16 v201, v208 offset:432
	ds_write_b16_d16_hi v201, v208 offset:496
	v_mul_f32_e32 v206, v84, v217
	v_mul_f32_e32 v207, v68, v217
	v_cvt_pk_bf16_f32 v206, v206, v207
	ds_write_b16 v201, v206 offset:1152
	ds_write_b16_d16_hi v201, v206 offset:1216
	v_mul_f32_e32 v208, v85, v218
	v_mul_f32_e32 v209, v69, v218
	v_cvt_pk_bf16_f32 v208, v208, v209
	ds_write_b16 v201, v208 offset:1296
	ds_write_b16_d16_hi v201, v208 offset:1360
	v_mul_f32_e32 v206, v86, v219
	v_mul_f32_e32 v207, v70, v219
	v_cvt_pk_bf16_f32 v206, v206, v207
	ds_write_b16 v201, v206 offset:1440
	ds_write_b16_d16_hi v201, v206 offset:1504
	v_mul_f32_e32 v208, v87, v220
	v_mul_f32_e32 v209, v71, v220
	v_cvt_pk_bf16_f32 v208, v208, v209
	ds_write_b16 v201, v208 offset:1584
	ds_write_b16_d16_hi v201, v208 offset:1648
	v_mul_f32_e32 v206, v88, v221
	v_mul_f32_e32 v207, v72, v221
	v_cvt_pk_bf16_f32 v206, v206, v207
	ds_write_b16 v201, v206 offset:2304
	ds_write_b16_d16_hi v201, v206 offset:2368
	v_mul_f32_e32 v208, v89, v222
	v_mul_f32_e32 v209, v73, v222
	v_cvt_pk_bf16_f32 v208, v208, v209
	ds_write_b16 v201, v208 offset:2448
	ds_write_b16_d16_hi v201, v208 offset:2512
	v_mul_f32_e32 v206, v90, v223
	v_mul_f32_e32 v207, v74, v223
	v_cvt_pk_bf16_f32 v206, v206, v207
	ds_write_b16 v201, v206 offset:2592
	ds_write_b16_d16_hi v201, v206 offset:2656
	v_mul_f32_e32 v208, v91, v224
	v_mul_f32_e32 v209, v75, v224
	v_cvt_pk_bf16_f32 v208, v208, v209
	ds_write_b16 v201, v208 offset:2736
	ds_write_b16_d16_hi v201, v208 offset:2800
	v_mul_f32_e32 v206, v92, v225
	v_mul_f32_e32 v207, v76, v225
	v_cvt_pk_bf16_f32 v206, v206, v207
	ds_write_b16 v201, v206 offset:3456
	ds_write_b16_d16_hi v201, v206 offset:3520
	v_mul_f32_e32 v208, v93, v226
	v_mul_f32_e32 v209, v77, v226
	v_cvt_pk_bf16_f32 v208, v208, v209
	ds_write_b16 v201, v208 offset:3600
	ds_write_b16_d16_hi v201, v208 offset:3664
	v_mul_f32_e32 v206, v94, v227
	v_mul_f32_e32 v207, v78, v227
	v_cvt_pk_bf16_f32 v206, v206, v207
	ds_write_b16 v201, v206 offset:3744
	ds_write_b16_d16_hi v201, v206 offset:3808
	v_mul_f32_e32 v208, v95, v228
	v_mul_f32_e32 v209, v79, v228
	v_cvt_pk_bf16_f32 v208, v208, v209
	ds_write_b16 v201, v208 offset:3888
	ds_write_b16_d16_hi v201, v208 offset:3952
.Lmq3k_e01_st:
	v_mad_u32_u24 v211, v204, s99, v205
	s_lshl_b32 s99, s99, 3
	ds_read_b128 v[160:163], v202
	ds_read_b128 v[164:167], v202 offset:1152
	ds_read_b128 v[168:171], v202 offset:2304
	ds_read_b128 v[172:175], v202 offset:3456
	v_add_u32_e32 v206, s89, v211
	s_add_u32 s89, s89, s99
	v_add_u32_e32 v207, s89, v211
	s_add_u32 s89, s89, s99
	v_add_u32_e32 v208, s89, v211
	s_add_u32 s89, s89, s99
	v_add_u32_e32 v209, s89, v211
	s_waitcnt lgkmcnt(3)
	global_store_dwordx4 v206, v[160:163], s[2:3]
	s_waitcnt lgkmcnt(2)
	global_store_dwordx4 v207, v[164:167], s[2:3]
	s_waitcnt lgkmcnt(1)
	global_store_dwordx4 v208, v[168:171], s[2:3]
	s_waitcnt lgkmcnt(0)
	global_store_dwordx4 v209, v[172:175], s[2:3]
	s_add_u32 s94, s92, 32
	s_add_u32 s95, s93, 0
	s_lshr_b32 s90, s95, 6
	s_lshr_b32 s96, s94, 12
	s_and_b32 s97, s94, 0xfff
	s_lshr_b32 s91, s90, 2
	s_and_b32 s98, s90, 3
	s_cmp_lt_u32 s98, 2
	s_cbranch_scc0 .Lmq3k_e10_v
	s_mul_i32 s89, s96, 0xc00000
	s_mul_i32 s91, s91, 0x180000
	s_add_u32 s89, s89, s91
	s_lshl_b32 s91, s98, 7
	s_add_u32 s89, s89, s91
	s_mul_i32 s91, s97, 0x180
	s_add_u32 s89, s89, s91
	s_movk_i32 s99, 0x180
	s_mov_b64 s[2:3], s[12:13]
	s_branch .Lmq3k_e10_plain

.Lmq3k_e10_plain:
	v_mul_f32_e32 v206, v48, v229
	v_mul_f32_e32 v207, v32, v229
	v_cvt_pk_bf16_f32 v206, v206, v207
	ds_write_b16 v201, v206
	ds_write_b16_d16_hi v201, v206 offset:64
	v_mul_f32_e32 v208, v49, v230
	v_mul_f32_e32 v209, v33, v230
	v_cvt_pk_bf16_f32 v208, v208, v209
	ds_write_b16 v201, v208 offset:144
	ds_write_b16_d16_hi v201, v208 offset:208
	v_mul_f32_e32 v206, v50, v231
	v_mul_f32_e32 v207, v34, v231
	v_cvt_pk_bf16_f32 v206, v206, v207
	ds_write_b16 v201, v206 offset:288
	ds_write_b16_d16_hi v201, v206 offset:352
	v_mul_f32_e32 v208, v51, v232
	v_mul_f32_e32 v209, v35, v232
	v_cvt_pk_bf16_f32 v208, v208, v209
	ds_write_b16 v201, v208 offset:432
	ds_write_b16_d16_hi v201, v208 offset:496
	v_mul_f32_e32 v206, v52, v233
	v_mul_f32_e32 v207, v36, v233
	v_cvt_pk_bf16_f32 v206, v206, v207
	ds_write_b16 v201, v206 offset:1152
	ds_write_b16_d16_hi v201, v206 offset:1216
	v_mul_f32_e32 v208, v53, v234
	v_mul_f32_e32 v209, v37, v234
	v_cvt_pk_bf16_f32 v208, v208, v209
	ds_write_b16 v201, v208 offset:1296
	ds_write_b16_d16_hi v201, v208 offset:1360
	v_mul_f32_e32 v206, v54, v235
	v_mul_f32_e32 v207, v38, v235
	v_cvt_pk_bf16_f32 v206, v206, v207
	ds_write_b16 v201, v206 offset:1440
	ds_write_b16_d16_hi v201, v206 offset:1504
	v_mul_f32_e32 v208, v55, v236
	v_mul_f32_e32 v209, v39, v236
	v_cvt_pk_bf16_f32 v208, v208, v209
	ds_write_b16 v201, v208 offset:1584
	ds_write_b16_d16_hi v201, v208 offset:1648
	v_mul_f32_e32 v206, v56, v237
	v_mul_f32_e32 v207, v40, v237
	v_cvt_pk_bf16_f32 v206, v206, v207
	ds_write_b16 v201, v206 offset:2304
	ds_write_b16_d16_hi v201, v206 offset:2368
	v_mul_f32_e32 v208, v57, v238
	v_mul_f32_e32 v209, v41, v238
	v_cvt_pk_bf16_f32 v208, v208, v209
	ds_write_b16 v201, v208 offset:2448
	ds_write_b16_d16_hi v201, v208 offset:2512
	v_mul_f32_e32 v206, v58, v239
	v_mul_f32_e32 v207, v42, v239
	v_cvt_pk_bf16_f32 v206, v206, v207
	ds_write_b16 v201, v206 offset:2592
	ds_write_b16_d16_hi v201, v206 offset:2656
	v_mul_f32_e32 v208, v59, v240
	v_mul_f32_e32 v209, v43, v240
	v_cvt_pk_bf16_f32 v208, v208, v209
	ds_write_b16 v201, v208 offset:2736
	ds_write_b16_d16_hi v201, v208 offset:2800
	v_mul_f32_e32 v206, v60, v241
	v_mul_f32_e32 v207, v44, v241
	v_cvt_pk_bf16_f32 v206, v206, v207
	ds_write_b16 v201, v206 offset:3456
	ds_write_b16_d16_hi v201, v206 offset:3520
	v_mul_f32_e32 v208, v61, v242
	v_mul_f32_e32 v209, v45, v242
	v_cvt_pk_bf16_f32 v208, v208, v209
	ds_write_b16 v201, v208 offset:3600
	ds_write_b16_d16_hi v201, v208 offset:3664
	v_mul_f32_e32 v206, v62, v243
	v_mul_f32_e32 v207, v46, v243
	v_cvt_pk_bf16_f32 v206, v206, v207
	ds_write_b16 v201, v206 offset:3744
	ds_write_b16_d16_hi v201, v206 offset:3808
	v_mul_f32_e32 v208, v63, v244
	v_mul_f32_e32 v209, v47, v244
	v_cvt_pk_bf16_f32 v208, v208, v209
	ds_write_b16 v201, v208 offset:3888
	ds_write_b16_d16_hi v201, v208 offset:3952
.Lmq3k_e10_st:
	v_mad_u32_u24 v211, v204, s99, v205
	s_lshl_b32 s99, s99, 3
	ds_read_b128 v[160:163], v202
	ds_read_b128 v[164:167], v202 offset:1152
	ds_read_b128 v[168:171], v202 offset:2304
	ds_read_b128 v[172:175], v202 offset:3456
	v_add_u32_e32 v206, s89, v211
	s_add_u32 s89, s89, s99
	v_add_u32_e32 v207, s89, v211
	s_add_u32 s89, s89, s99
	v_add_u32_e32 v208, s89, v211
	s_add_u32 s89, s89, s99
	v_add_u32_e32 v209, s89, v211
	s_waitcnt lgkmcnt(3)
	global_store_dwordx4 v206, v[160:163], s[2:3]
	s_waitcnt lgkmcnt(2)
	global_store_dwordx4 v207, v[164:167], s[2:3]
	s_waitcnt lgkmcnt(1)
	global_store_dwordx4 v208, v[168:171], s[2:3]
	s_waitcnt lgkmcnt(0)
	global_store_dwordx4 v209, v[172:175], s[2:3]
	s_add_u32 s94, s92, 32
	s_add_u32 s95, s93, 64
	s_lshr_b32 s90, s95, 6
	s_lshr_b32 s96, s94, 12
	s_and_b32 s97, s94, 0xfff
	s_lshr_b32 s91, s90, 2
	s_and_b32 s98, s90, 3
	s_cmp_lt_u32 s98, 2
	s_cbranch_scc0 .Lmq3k_e11_v
	s_mul_i32 s89, s96, 0xc00000
	s_mul_i32 s91, s91, 0x180000
	s_add_u32 s89, s89, s91
	s_lshl_b32 s91, s98, 7
	s_add_u32 s89, s89, s91
	s_mul_i32 s91, s97, 0x180
	s_add_u32 s89, s89, s91
	s_movk_i32 s99, 0x180
	s_mov_b64 s[2:3], s[12:13]
	s_branch .Lmq3k_e11_plain

.Lmq3k_e11_plain:
	v_mul_f32_e32 v206, v16, v229
	v_mul_f32_e32 v207, v0, v229
	v_cvt_pk_bf16_f32 v206, v206, v207
	ds_write_b16 v201, v206
	ds_write_b16_d16_hi v201, v206 offset:64
	v_mul_f32_e32 v208, v17, v230
	v_mul_f32_e32 v209, v1, v230
	v_cvt_pk_bf16_f32 v208, v208, v209
	ds_write_b16 v201, v208 offset:144
	ds_write_b16_d16_hi v201, v208 offset:208
	v_mul_f32_e32 v206, v18, v231
	v_mul_f32_e32 v207, v2, v231
	v_cvt_pk_bf16_f32 v206, v206, v207
	ds_write_b16 v201, v206 offset:288
	ds_write_b16_d16_hi v201, v206 offset:352
	v_mul_f32_e32 v208, v19, v232
	v_mul_f32_e32 v209, v3, v232
	v_cvt_pk_bf16_f32 v208, v208, v209
	ds_write_b16 v201, v208 offset:432
	ds_write_b16_d16_hi v201, v208 offset:496
	v_mul_f32_e32 v206, v20, v233
	v_mul_f32_e32 v207, v4, v233
	v_cvt_pk_bf16_f32 v206, v206, v207
	ds_write_b16 v201, v206 offset:1152
	ds_write_b16_d16_hi v201, v206 offset:1216
	v_mul_f32_e32 v208, v21, v234
	v_mul_f32_e32 v209, v5, v234
	v_cvt_pk_bf16_f32 v208, v208, v209
	ds_write_b16 v201, v208 offset:1296
	ds_write_b16_d16_hi v201, v208 offset:1360
	v_mul_f32_e32 v206, v22, v235
	v_mul_f32_e32 v207, v6, v235
	v_cvt_pk_bf16_f32 v206, v206, v207
	ds_write_b16 v201, v206 offset:1440
	ds_write_b16_d16_hi v201, v206 offset:1504
	v_mul_f32_e32 v208, v23, v236
	v_mul_f32_e32 v209, v7, v236
	v_cvt_pk_bf16_f32 v208, v208, v209
	ds_write_b16 v201, v208 offset:1584
	ds_write_b16_d16_hi v201, v208 offset:1648
	v_mul_f32_e32 v206, v24, v237
	v_mul_f32_e32 v207, v8, v237
	v_cvt_pk_bf16_f32 v206, v206, v207
	ds_write_b16 v201, v206 offset:2304
	ds_write_b16_d16_hi v201, v206 offset:2368
	v_mul_f32_e32 v208, v25, v238
	v_mul_f32_e32 v209, v9, v238
	v_cvt_pk_bf16_f32 v208, v208, v209
	ds_write_b16 v201, v208 offset:2448
	ds_write_b16_d16_hi v201, v208 offset:2512
	v_mul_f32_e32 v206, v26, v239
	v_mul_f32_e32 v207, v10, v239
	v_cvt_pk_bf16_f32 v206, v206, v207
	ds_write_b16 v201, v206 offset:2592
	ds_write_b16_d16_hi v201, v206 offset:2656
	v_mul_f32_e32 v208, v27, v240
	v_mul_f32_e32 v209, v11, v240
	v_cvt_pk_bf16_f32 v208, v208, v209
	ds_write_b16 v201, v208 offset:2736
	ds_write_b16_d16_hi v201, v208 offset:2800
	v_mul_f32_e32 v206, v28, v241
	v_mul_f32_e32 v207, v12, v241
	v_cvt_pk_bf16_f32 v206, v206, v207
	ds_write_b16 v201, v206 offset:3456
	ds_write_b16_d16_hi v201, v206 offset:3520
	v_mul_f32_e32 v208, v29, v242
	v_mul_f32_e32 v209, v13, v242
	v_cvt_pk_bf16_f32 v208, v208, v209
	ds_write_b16 v201, v208 offset:3600
	ds_write_b16_d16_hi v201, v208 offset:3664
	v_mul_f32_e32 v206, v30, v243
	v_mul_f32_e32 v207, v14, v243
	v_cvt_pk_bf16_f32 v206, v206, v207
	ds_write_b16 v201, v206 offset:3744
	ds_write_b16_d16_hi v201, v206 offset:3808
	v_mul_f32_e32 v208, v31, v244
	v_mul_f32_e32 v209, v15, v244
	v_cvt_pk_bf16_f32 v208, v208, v209
	ds_write_b16 v201, v208 offset:3888
	ds_write_b16_d16_hi v201, v208 offset:3952
.Lmq3k_e11_st:
	v_mad_u32_u24 v211, v204, s99, v205
	s_lshl_b32 s99, s99, 3
	ds_read_b128 v[160:163], v202
	ds_read_b128 v[164:167], v202 offset:1152
	ds_read_b128 v[168:171], v202 offset:2304
	ds_read_b128 v[172:175], v202 offset:3456
	v_add_u32_e32 v206, s89, v211
	s_add_u32 s89, s89, s99
	v_add_u32_e32 v207, s89, v211
	s_add_u32 s89, s89, s99
	v_add_u32_e32 v208, s89, v211
	s_add_u32 s89, s89, s99
	v_add_u32_e32 v209, s89, v211
	s_waitcnt lgkmcnt(3)
	global_store_dwordx4 v206, v[160:163], s[2:3]
	s_waitcnt lgkmcnt(2)
	global_store_dwordx4 v207, v[164:167], s[2:3]
	s_waitcnt lgkmcnt(1)
	global_store_dwordx4 v208, v[168:171], s[2:3]
	s_waitcnt lgkmcnt(0)
	global_store_dwordx4 v209, v[172:175], s[2:3]
	s_add_u32 s30, s30, s42
	s_cmp_lt_u32 s30, 1024
	s_cbranch_scc1 .Lmq3k_tile
.Lmq3k_done:
.LBB0_1140:
	s_cmp_lt_i32 s45, 5
	s_cbranch_scc1 .LBB0_1194
	s_waitcnt vmcnt(0)
	v_cmp_eq_u32_e32 vcc, 0, v206
	s_waitcnt lgkmcnt(0)
	s_and_b64 s[4:5], s[46:47], vcc
	s_waitcnt vmcnt(63) expcnt(7) lgkmcnt(15)
	s_barrier
	s_and_saveexec_b64 s[2:3], s[4:5]
	s_cbranch_execz .LBB0_1193
	v_mov_b32_e32 v0, 0x24400
	s_waitcnt vmcnt(0) expcnt(0) lgkmcnt(0)
	ds_read_b32 v2, v0
	v_mov_b32_e32 v0, 0x24404
	ds_read_b32 v0, v0
	s_waitcnt lgkmcnt(1)
	v_cmp_ne_u32_e32 vcc, 0, v2
	s_cbranch_vccnz .LBB0_1157
	s_add_u32 s4, s40, 0x1000
	s_addc_u32 s5, s41, 0
	s_add_u32 s6, s40, 0x1100
	s_addc_u32 s7, s41, 0
	s_add_u32 s8, s40, 0x1200
	s_addc_u32 s9, s41, 0
	s_mul_i32 s18, s43, s33
	s_add_u32 s10, s40, 0x1300
	s_mul_i32 s18, s18, s42
	s_addc_u32 s11, s41, 0
	s_mov_b32 s19, 1
	v_mov_b32_e32 v16, 0
	s_branch .LBB0_1145

.LBB0_5230:
	s_cmp_gt_i32 s44, 19
	s_waitcnt lgkmcnt(0)
	s_cselect_b64 s[2:3], -1, 0
	s_cmp_lt_i32 s45, 20
	s_cselect_b64 s[4:5], -1, 0
	s_or_b64 s[2:3], s[2:3], s[4:5]
	s_and_b64 vcc, exec, s[2:3]
	s_cbranch_vccnz .LBB0_5559
	s_mov_b32 s28, s22
	s_and_b32 s2, s42, 7
	s_cmp_lg_u32 s2, 0
	s_cbranch_scc1 .Lmq19_vb
	s_and_b32 s2, s22, 7
	s_ashr_i32 s3, s42, 3
	s_mul_i32 s2, s3, s2
	s_ashr_i32 s3, s22, 3
	s_add_i32 s28, s2, s3
.Lmq19_vb:
	v_mbcnt_hi_u32_b32 v206, -1, v210
	s_lshr_b32 s29, s70, 6
	s_lshl_b32 s88, s70, 4
	s_and_b32 s90, s70, 0x40
	v_and_b32_e32 v245, 48, v206
	v_or_b32_e32 v245, s90, v245
	v_and_b32_e32 v207, 31, v206
	v_lshrrev_b32_e32 v208, 5, v206
	v_bfe_u32 v209, v206, 1, 3
	v_lshlrev_b32_e32 v211, 7, v207
	s_lshr_b32 s91, s70, 7
	s_lshl_b32 s31, s91, 6
	s_lshl_b32 s91, s91, 13
	s_lshl_b32 s34, s90, 1
	s_lshl_b32 s90, s90, 8
	s_add_u32 s90, s90, 0x8000
	v_xor_b32_e32 v212, v208, v209
	v_lshl_add_u32 v212, v212, 4, v211
	v_add_u32_e32 v184, s91, v212
	v_add_u32_e32 v188, s90, v212
	v_or_b32_e32 v212, 2, v208
	v_xor_b32_e32 v212, v212, v209
	v_lshl_add_u32 v212, v212, 4, v211
	v_add_u32_e32 v185, s91, v212
	v_add_u32_e32 v189, s90, v212
	v_or_b32_e32 v212, 4, v208
	v_xor_b32_e32 v212, v212, v209
	v_lshl_add_u32 v212, v212, 4, v211
	v_add_u32_e32 v186, s91, v212
	v_add_u32_e32 v190, s90, v212
	v_or_b32_e32 v212, 6, v208
	v_xor_b32_e32 v212, v212, v209
	v_lshl_add_u32 v212, v212, 4, v211
	v_add_u32_e32 v187, s91, v212
	v_add_u32_e32 v191, s90, v212
	v_lshlrev_b32_e32 v200, 3, v207
	v_lshlrev_b32_e32 v203, 2, v208
	s_mul_i32 s91, s29, 0x1200
	s_add_u32 s91, s91, 0x12000
	v_mul_u32_u24_e32 v212, 0x240, v208
	v_lshl_add_u32 v212, v207, 1, v212
	v_add_u32_e32 v201, s91, v212
	v_lshrrev_b32_e32 v204, 3, v206
	v_and_b32_e32 v212, 7, v206
	v_lshlrev_b32_e32 v205, 4, v212
	v_mul_u32_u24_e32 v212, 0x90, v204
	v_add3_u32 v202, v212, v205, s91
	s_load_dwordx2 s[4:5], s[0:1], 0x168
	s_load_dwordx2 s[6:7], s[0:1], 0xd8
	s_load_dwordx2 s[8:9], s[0:1], 0x210
	s_load_dwordx2 s[10:11], s[0:1], 0x148
	s_load_dwordx2 s[12:13], s[0:1], 0x178
	s_lshl_b32 s96, s29, 3
	v_add_u32_e32 v206, s96, v204
	v_xor_b32_e32 v207, v245, v205
	v_lshl_add_u32 v192, v206, 9, v207
	v_mov_b32_e32 v193, 0
	v_add_u32_e32 v208, 64, v206
	v_lshl_add_u32 v194, v208, 9, v207
	v_mov_b32_e32 v195, 0
	v_add_u32_e32 v208, 128, v206
	v_lshl_add_u32 v196, v208, 9, v207
	v_mov_b32_e32 v197, 0
	v_add_u32_e32 v208, 192, v206
	v_lshl_add_u32 v198, v208, 9, v207
	v_mov_b32_e32 v199, 0
	s_mov_b32 s30, s28
	s_cmp_ge_u32 s30, 768
	s_cbranch_scc1 .Lmq19q_done
	s_waitcnt lgkmcnt(0)
	s_mul_hi_u32 s35, s30, 0xaaaaaaab
	s_lshr_b32 s35, s35, 2
	s_mul_i32 s36, s35, 6
	s_sub_u32 s36, s30, s36
	s_lshl_b32 s98, s35, 17
	s_add_u32 s16, s4, s98
	s_addc_u32 s17, s5, 0
	s_lshl_b32 s98, s36, 17
	s_add_u32 s18, s6, s98
	s_addc_u32 s19, s7, 0
	s_add_u32 m0, s88, 0
	v_lshl_add_u64 v[152:153], v[192:193], 0, s[16:17]
	global_load_lds_dwordx4 v[152:153], off
	s_add_u32 m0, s88, 32768
	v_lshl_add_u64 v[154:155], v[192:193], 0, s[18:19]
	global_load_lds_dwordx4 v[154:155], off
	s_add_u32 m0, s88, 8192
	v_lshl_add_u64 v[156:157], v[194:195], 0, s[16:17]
	global_load_lds_dwordx4 v[156:157], off
	s_add_u32 m0, s88, 40960
	v_lshl_add_u64 v[152:153], v[194:195], 0, s[18:19]
	global_load_lds_dwordx4 v[152:153], off
	s_add_u32 m0, s88, 16384
	v_lshl_add_u64 v[154:155], v[196:197], 0, s[16:17]
	global_load_lds_dwordx4 v[154:155], off
	s_add_u32 m0, s88, 49152
	v_lshl_add_u64 v[156:157], v[196:197], 0, s[18:19]
	global_load_lds_dwordx4 v[156:157], off
	s_add_u32 m0, s88, 24576
	v_lshl_add_u64 v[152:153], v[198:199], 0, s[16:17]
	global_load_lds_dwordx4 v[152:153], off
	s_add_u32 m0, s88, 57344
	v_lshl_add_u64 v[154:155], v[198:199], 0, s[18:19]
	global_load_lds_dwordx4 v[154:155], off

.Lmq19q_done:
	s_load_dwordx2 s[4:5], s[0:1], 0x170
	s_load_dwordx2 s[6:7], s[0:1], 0xe8
	s_load_dwordx2 s[8:9], s[0:1], 0x218
	s_load_dwordx2 s[10:11], s[0:1], 0x148
	s_load_dwordx2 s[12:13], s[0:1], 0x180
	s_load_dwordx2 s[14:15], s[0:1], 0x188
	s_lshl_b32 s96, s29, 3
	v_add_u32_e32 v206, s96, v204
	v_xor_b32_e32 v207, v245, v205
	v_lshl_add_u32 v192, v206, 8, v207
	v_mov_b32_e32 v193, 0
	v_add_u32_e32 v208, 64, v206
	v_lshl_add_u32 v194, v208, 8, v207
	v_mov_b32_e32 v195, 0
	v_add_u32_e32 v208, 128, v206
	v_lshl_add_u32 v196, v208, 8, v207
	v_mov_b32_e32 v197, 0
	v_add_u32_e32 v208, 192, v206
	v_lshl_add_u32 v198, v208, 8, v207
	v_mov_b32_e32 v199, 0
	s_mov_b32 s30, s28
	s_cmp_ge_u32 s30, 1024
	s_cbranch_scc1 .Lmq19k_done
	s_waitcnt lgkmcnt(0)
	s_lshr_b32 s35, s30, 3
	s_mul_i32 s36, s35, 8
	s_sub_u32 s36, s30, s36
	s_lshl_b32 s98, s35, 16
	s_add_u32 s16, s4, s98
	s_addc_u32 s17, s5, 0
	s_lshl_b32 s98, s36, 16
	s_add_u32 s18, s6, s98
	s_addc_u32 s19, s7, 0
	s_add_u32 m0, s88, 0
	v_lshl_add_u64 v[152:153], v[192:193], 0, s[16:17]
	global_load_lds_dwordx4 v[152:153], off
	s_add_u32 m0, s88, 32768
	v_lshl_add_u64 v[154:155], v[192:193], 0, s[18:19]
	global_load_lds_dwordx4 v[154:155], off
	s_add_u32 m0, s88, 8192
	v_lshl_add_u64 v[156:157], v[194:195], 0, s[16:17]
	global_load_lds_dwordx4 v[156:157], off
	s_add_u32 m0, s88, 40960
	v_lshl_add_u64 v[152:153], v[194:195], 0, s[18:19]
	global_load_lds_dwordx4 v[152:153], off
	s_add_u32 m0, s88, 16384
	v_lshl_add_u64 v[154:155], v[196:197], 0, s[16:17]
	global_load_lds_dwordx4 v[154:155], off
	s_add_u32 m0, s88, 49152
	v_lshl_add_u64 v[156:157], v[196:197], 0, s[18:19]
	global_load_lds_dwordx4 v[156:157], off
	s_add_u32 m0, s88, 24576
	v_lshl_add_u64 v[152:153], v[198:199], 0, s[16:17]
	global_load_lds_dwordx4 v[152:153], off
	s_add_u32 m0, s88, 57344
	v_lshl_add_u64 v[154:155], v[198:199], 0, s[18:19]
	global_load_lds_dwordx4 v[154:155], off

.Lmq19k_done:
.LBB0_5505:
	s_cmp_lt_i32 s45, 21
	s_cbranch_scc1 .LBB0_5559
	s_waitcnt vmcnt(0)
	v_cmp_eq_u32_e32 vcc, 0, v206
	s_waitcnt lgkmcnt(0)
	s_and_b64 s[4:5], s[46:47], vcc
	s_waitcnt vmcnt(63) expcnt(7) lgkmcnt(15)
	s_barrier
	s_and_saveexec_b64 s[2:3], s[4:5]
	s_cbranch_execz .LBB0_5558
	v_mov_b32_e32 v0, 0x24400
	s_waitcnt vmcnt(0) expcnt(0) lgkmcnt(0)
	ds_read_b32 v2, v0
	v_mov_b32_e32 v0, 0x24404
	ds_read_b32 v0, v0
	s_waitcnt lgkmcnt(1)
	v_cmp_ne_u32_e32 vcc, 0, v2
	s_cbranch_vccnz .LBB0_5522
	s_add_u32 s4, s40, 0x1000
	s_addc_u32 s5, s41, 0
	s_add_u32 s6, s40, 0x1100
	s_addc_u32 s7, s41, 0
	s_add_u32 s8, s40, 0x1200
	s_addc_u32 s9, s41, 0
	s_mul_i32 s18, s43, s33
	s_add_u32 s10, s40, 0x1300
	s_mul_i32 s18, s18, s42
	s_addc_u32 s11, s41, 0
	s_mov_b32 s19, 1
	v_mov_b32_e32 v16, 0
	s_branch .LBB0_5510
